# all five GEMM K-loops: LDS-DMA addresses formed in saddr form (SGPR base + 32-bit lane offset) instead of a 64-bit VALU add per load; scalar adds for the +kstep variants
# baseline (speedup 1.0000x reference)
; #define PG8_STAGE(bufoff, gbase, voff) do { _Pragma("unroll") for (int _i = 0; _i < 2; ++_i) \
;     __builtin_amdgcn_global_load_lds((const unsigned*)((const char*)(gbase) + (voff)[_i]), (PG8_LAS unsigned*)(lds + (bufoff) + ldsw + _i * 8192), 16, 0, 0); } while (0)
; #define PG8_LDA(dst, b, h) do { _Pragma("unroll") for (int m = 0; m < 4; ++m) _Pragma("unroll") for (int k = 0; k < 2; ++k) dst[m][k] = *(const PG8_LAS bf16x8*)(lds + PG8_SA(b, h) + aoff + m * 2048 + k * 1024); } while (0)
; #define PG8_LDB(dst, b, h) do { _Pragma("unroll") for (int n = 0; n < 2; ++n) _Pragma("unroll") for (int k = 0; k < 2; ++k) dst[n][k] = *(const PG8_LAS bf16x8*)(lds + PG8_SB(b, h) + boff + n * 2048 + k * 1024); } while (0)
; #define PG8_MMA(ai, bj, At, Bt) do { __builtin_amdgcn_s_setprio(1); _Pragma("unroll") for (int m = 0; m < 4; ++m) _Pragma("unroll") for (int n = 0; n < 2; ++n) _Pragma("unroll") for (int k = 0; k < 2; ++k) \
;     acc[ai][bj][m][n] = __builtin_amdgcn_mfma_f32_16x16x32_bf16(Bt[n][k], At[m][k], acc[ai][bj][m][n], 0, 0, 0); __builtin_amdgcn_s_setprio(0); } while (0)
; #define PG8_WAIT_V(n) asm volatile("s_waitcnt vmcnt(" #n ")" ::: "memory")
; #define PG8_WAIT_L(n) asm volatile("s_waitcnt lgkmcnt(" #n ")" ::: "memory")
; #define PG8_BAR __builtin_amdgcn_s_barrier()
; #define PG8_SCHED __builtin_amdgcn_sched_barrier(0)
; template <class Epi>
; DI void gemm_phase(const bf16_t* __restrict__ gA, const bf16_t* __restrict__ gBt, int M, int N, int K, const Epi& E, char* lds_generic) {
;     ...
;       const bool last = (t == nt - 2);
;       const char* a1 = cA + (size_t)(t + 1) * kstep;
;       const char* a2 = last ? nA : cA + (size_t)(t + 2) * kstep; const char* b2 = last ? nB : cB + (size_t)(t + 2) * kstep;
;       const char* a3 = a2 + kstep; const char* b3 = b2 + kstep;
;       PG8_LDB(B0, 0, 0); PG8_SCHED; PG8_LDA(At, 0, 0); PG8_STAGE(PG8_SA(1, 1), a1 + hstep, voffA);
;       PG8_WAIT_L(8); PG8_BAR; PG8_WAIT_L(0); PG8_MMA(0, 0, At, B0); PG8_BAR; PG8_SCHED;
;       PG8_LDB(B1, 0, 1); PG8_STAGE(PG8_SB(0, 0), b2, voffB);
;       PG8_BAR; PG8_WAIT_L(0); PG8_MMA(0, 1, At, B1); PG8_BAR;
;       PG8_LDA(At, 0, 1); PG8_STAGE(PG8_SA(0, 0), a2, voffA);
;       PG8_BAR; PG8_WAIT_L(0); PG8_MMA(1, 0, At, B0); PG8_BAR; PG8_SCHED;
;       PG8_STAGE(PG8_SB(0, 1), b2 + hstep, voffB);
;       PG8_WAIT_V(6); PG8_BAR; PG8_MMA(1, 1, At, B1); PG8_BAR;
.LBB0_137:
	ds_read_b128 v[130:133], v157
	ds_read_b128 v[146:149], v158
	ds_read_b128 v[176:179], v159
	ds_read_b128 v[180:183], v160
	s_add_u32 s24, s80, 0xfffc0080
	s_addc_u32 s25, s81, -1
	s_cmp_eq_u32 s62, 12
	s_cselect_b32 s31, s22, s25
	s_cselect_b32 s30, s23, s24
	s_cselect_b32 s29, s1, s61
	s_cselect_b32 s28, s27, s60
	s_mov_b32 m0, s33
	ds_read_b128 v[184:187], v154
	ds_read_b128 v[188:191], v154 offset:1024
	ds_read_b128 v[192:195], v154 offset:2048
	ds_read_b128 v[196:199], v154 offset:3072
	ds_read_b128 v[200:203], v154 offset:4096
	ds_read_b128 v[204:207], v154 offset:5120
	ds_read_b128 v[208:211], v154 offset:6144
	ds_read_b128 v[212:215], v154 offset:7168
	global_load_lds_dwordx4 v142, s[80:81]
	s_mov_b32 m0, s35
	s_nop 0
	global_load_lds_dwordx4 v144, s[80:81]
	s_barrier
	s_waitcnt lgkmcnt(0)
	s_waitcnt lgkmcnt(0)
	v_mfma_f32_16x16x32_bf16 v[126:129], v[130:133], v[184:187], v[126:129]
	v_mfma_f32_16x16x32_bf16 v[122:125], v[176:179], v[184:187], v[122:125]
	v_mfma_f32_16x16x32_bf16 v[118:121], v[130:133], v[192:195], v[118:121]
	v_mfma_f32_16x16x32_bf16 v[110:113], v[176:179], v[192:195], v[110:113]
	v_mfma_f32_16x16x32_bf16 v[98:101], v[130:133], v[200:203], v[98:101]
	v_mfma_f32_16x16x32_bf16 v[90:93], v[176:179], v[200:203], v[90:93]
	v_mfma_f32_16x16x32_bf16 v[86:89], v[130:133], v[208:211], v[86:89]
	v_mfma_f32_16x16x32_bf16 v[78:81], v[176:179], v[208:211], v[78:81]
	v_mfma_f32_16x16x32_bf16 v[126:129], v[146:149], v[188:191], v[126:129]
	v_mfma_f32_16x16x32_bf16 v[122:125], v[180:183], v[188:191], v[122:125]
	v_mfma_f32_16x16x32_bf16 v[118:121], v[146:149], v[196:199], v[118:121]
	v_mfma_f32_16x16x32_bf16 v[110:113], v[180:183], v[196:199], v[110:113]
	v_mfma_f32_16x16x32_bf16 v[98:101], v[146:149], v[204:207], v[98:101]
	v_mfma_f32_16x16x32_bf16 v[90:93], v[180:183], v[204:207], v[90:93]
	v_mfma_f32_16x16x32_bf16 v[86:89], v[146:149], v[212:215], v[86:89]
	v_mfma_f32_16x16x32_bf16 v[78:81], v[180:183], v[212:215], v[78:81]
	s_barrier
	s_mov_b32 m0, s6
	ds_read_b128 v[216:219], v161
	ds_read_b128 v[238:241], v163
	ds_read_b128 v[242:245], v165
	ds_read_b128 v[246:249], v166
	global_load_lds_dwordx4 v0, s[28:29]
	s_mov_b32 m0, s7
	s_nop 0
	global_load_lds_dwordx4 v138, s[28:29]
	s_barrier
	s_waitcnt lgkmcnt(0)
	s_waitcnt lgkmcnt(0)
	v_mfma_f32_16x16x32_bf16 v[114:117], v[216:219], v[184:187], v[114:117]
	v_mfma_f32_16x16x32_bf16 v[106:109], v[242:245], v[184:187], v[106:109]
	v_mfma_f32_16x16x32_bf16 v[102:105], v[216:219], v[192:195], v[102:105]
	v_mfma_f32_16x16x32_bf16 v[94:97], v[242:245], v[192:195], v[94:97]
	v_mfma_f32_16x16x32_bf16 v[82:85], v[216:219], v[200:203], v[82:85]
	v_mfma_f32_16x16x32_bf16 v[74:77], v[242:245], v[200:203], v[74:77]
	v_mfma_f32_16x16x32_bf16 v[70:73], v[216:219], v[208:211], v[70:73]
	v_mfma_f32_16x16x32_bf16 v[66:69], v[242:245], v[208:211], v[66:69]
	v_mfma_f32_16x16x32_bf16 v[114:117], v[238:241], v[188:191], v[114:117]
	v_mfma_f32_16x16x32_bf16 v[106:109], v[246:249], v[188:191], v[106:109]
	v_mfma_f32_16x16x32_bf16 v[102:105], v[238:241], v[196:199], v[102:105]
	v_mfma_f32_16x16x32_bf16 v[94:97], v[246:249], v[196:199], v[94:97]
	v_mfma_f32_16x16x32_bf16 v[82:85], v[238:241], v[204:207], v[82:85]
	v_mfma_f32_16x16x32_bf16 v[74:77], v[246:249], v[204:207], v[74:77]
	v_mfma_f32_16x16x32_bf16 v[70:73], v[238:241], v[212:215], v[70:73]
	v_mfma_f32_16x16x32_bf16 v[66:69], v[246:249], v[212:215], v[66:69]
	s_mov_b32 m0, s5
	s_barrier
	ds_read_b128 v[184:187], v154 offset:16384
	ds_read_b128 v[188:191], v154 offset:17408
	ds_read_b128 v[192:195], v154 offset:18432
	ds_read_b128 v[196:199], v154 offset:19456
	ds_read_b128 v[200:203], v154 offset:20480
	ds_read_b128 v[204:207], v154 offset:21504
	ds_read_b128 v[208:211], v154 offset:22528
	ds_read_b128 v[212:215], v154 offset:23552
	global_load_lds_dwordx4 v134, s[30:31]
	s_mov_b32 m0, s8
	s_nop 0
	global_load_lds_dwordx4 v136, s[30:31]
	s_barrier
	s_waitcnt lgkmcnt(0)
	s_waitcnt lgkmcnt(0)
	v_mfma_f32_16x16x32_bf16 v[62:65], v[130:133], v[184:187], v[62:65]
	v_mfma_f32_16x16x32_bf16 v[58:61], v[176:179], v[184:187], v[58:61]
	v_mfma_f32_16x16x32_bf16 v[54:57], v[130:133], v[192:195], v[54:57]
	v_mfma_f32_16x16x32_bf16 v[46:49], v[176:179], v[192:195], v[46:49]
	v_mfma_f32_16x16x32_bf16 v[34:37], v[130:133], v[200:203], v[34:37]
	v_mfma_f32_16x16x32_bf16 v[26:29], v[176:179], v[200:203], v[26:29]
	v_mfma_f32_16x16x32_bf16 v[22:25], v[130:133], v[208:211], v[22:25]
	v_mfma_f32_16x16x32_bf16 v[14:17], v[176:179], v[208:211], v[14:17]
	v_mfma_f32_16x16x32_bf16 v[62:65], v[146:149], v[188:191], v[62:65]
	v_mfma_f32_16x16x32_bf16 v[58:61], v[180:183], v[188:191], v[58:61]
	v_mfma_f32_16x16x32_bf16 v[54:57], v[146:149], v[196:199], v[54:57]
	v_mfma_f32_16x16x32_bf16 v[46:49], v[180:183], v[196:199], v[46:49]
	v_mfma_f32_16x16x32_bf16 v[34:37], v[146:149], v[204:207], v[34:37]
	v_mfma_f32_16x16x32_bf16 v[26:29], v[180:183], v[204:207], v[26:29]
	v_mfma_f32_16x16x32_bf16 v[22:25], v[146:149], v[212:215], v[22:25]
	v_mfma_f32_16x16x32_bf16 v[14:17], v[180:183], v[212:215], v[14:17]
	s_barrier
	s_add_u32 s82, s28, 0x40000
	s_addc_u32 s83, s29, 0
	s_mov_b32 m0, s9
	s_nop 0
	global_load_lds_dwordx4 v0, s[82:83]
	s_mov_b32 m0, s12
	s_nop 0
	global_load_lds_dwordx4 v138, s[82:83]
	s_waitcnt vmcnt(6)
	s_barrier
; #define PG8_STAGE(bufoff, gbase, voff) do { _Pragma("unroll") for (int _i = 0; _i < 2; ++_i) \
;     __builtin_amdgcn_global_load_lds((const unsigned*)((const char*)(gbase) + (voff)[_i]), (PG8_LAS unsigned*)(lds + (bufoff) + ldsw + _i * 8192), 16, 0, 0); } while (0)
; #define PG8_LDA(dst, b, h) do { _Pragma("unroll") for (int m = 0; m < 4; ++m) _Pragma("unroll") for (int k = 0; k < 2; ++k) dst[m][k] = *(const PG8_LAS bf16x8*)(lds + PG8_SA(b, h) + aoff + m * 2048 + k * 1024); } while (0)
; #define PG8_LDB(dst, b, h) do { _Pragma("unroll") for (int n = 0; n < 2; ++n) _Pragma("unroll") for (int k = 0; k < 2; ++k) dst[n][k] = *(const PG8_LAS bf16x8*)(lds + PG8_SB(b, h) + boff + n * 2048 + k * 1024); } while (0)
; #define PG8_MMA(ai, bj, At, Bt) do { __builtin_amdgcn_s_setprio(1); _Pragma("unroll") for (int m = 0; m < 4; ++m) _Pragma("unroll") for (int n = 0; n < 2; ++n) _Pragma("unroll") for (int k = 0; k < 2; ++k) \
;     acc[ai][bj][m][n] = __builtin_amdgcn_mfma_f32_16x16x32_bf16(Bt[n][k], At[m][k], acc[ai][bj][m][n], 0, 0, 0); __builtin_amdgcn_s_setprio(0); } while (0)
; #define PG8_WAIT_V(n) asm volatile("s_waitcnt vmcnt(" #n ")" ::: "memory")
; #define PG8_WAIT_L(n) asm volatile("s_waitcnt lgkmcnt(" #n ")" ::: "memory")
; #define PG8_BAR __builtin_amdgcn_s_barrier()
; #define PG8_SCHED __builtin_amdgcn_sched_barrier(0)
; template <class Epi>
; DI void gemm_phase(const bf16_t* __restrict__ gA, const bf16_t* __restrict__ gBt, int M, int N, int K, const Epi& E, char* lds_generic) {
;     ...
;       PG8_WAIT_V(6); PG8_BAR; PG8_MMA(1, 1, At, B1); PG8_BAR;
;       PG8_LDB(B0, 1, 0); PG8_SCHED; PG8_LDA(At, 1, 0); PG8_STAGE(PG8_SA(0, 1), a2 + hstep, voffA);
;       PG8_WAIT_L(8); PG8_BAR; PG8_WAIT_L(0); PG8_MMA(0, 0, At, B0); PG8_BAR; PG8_SCHED;
;       PG8_LDB(B1, 1, 1); PG8_STAGE(PG8_SB(1, 0), b3, voffB);
;       PG8_BAR; PG8_WAIT_L(0); PG8_MMA(0, 1, At, B1); PG8_BAR;
;       PG8_LDA(At, 1, 1); PG8_STAGE(PG8_SA(1, 0), a3, voffA);
	v_mfma_f32_16x16x32_bf16 v[50:53], v[216:219], v[184:187], v[50:53]
	v_mfma_f32_16x16x32_bf16 v[42:45], v[242:245], v[184:187], v[42:45]
	v_mfma_f32_16x16x32_bf16 v[38:41], v[216:219], v[192:195], v[38:41]
	v_mfma_f32_16x16x32_bf16 v[30:33], v[242:245], v[192:195], v[30:33]
	v_mfma_f32_16x16x32_bf16 v[18:21], v[216:219], v[200:203], v[18:21]
	v_mfma_f32_16x16x32_bf16 v[10:13], v[242:245], v[200:203], v[10:13]
	v_mfma_f32_16x16x32_bf16 v[6:9], v[216:219], v[208:211], v[6:9]
	v_mfma_f32_16x16x32_bf16 v[2:5], v[242:245], v[208:211], v[2:5]
	v_mfma_f32_16x16x32_bf16 v[50:53], v[238:241], v[188:191], v[50:53]
	v_mfma_f32_16x16x32_bf16 v[42:45], v[246:249], v[188:191], v[42:45]
	v_mfma_f32_16x16x32_bf16 v[38:41], v[238:241], v[196:199], v[38:41]
	v_mfma_f32_16x16x32_bf16 v[30:33], v[246:249], v[196:199], v[30:33]
	v_mfma_f32_16x16x32_bf16 v[18:21], v[238:241], v[204:207], v[18:21]
	v_mfma_f32_16x16x32_bf16 v[10:13], v[246:249], v[204:207], v[10:13]
	v_mfma_f32_16x16x32_bf16 v[6:9], v[238:241], v[212:215], v[6:9]
	v_mfma_f32_16x16x32_bf16 v[2:5], v[246:249], v[212:215], v[2:5]
	s_barrier
	ds_read_b128 v[130:133], v167
	ds_read_b128 v[146:149], v168
	ds_read_b128 v[176:179], v169
	ds_read_b128 v[180:183], v170
	s_add_u32 s30, s30, 0x40000
	s_addc_u32 s31, s31, 0
	s_mov_b32 m0, s13
	ds_read_b128 v[184:187], v154 offset:32768
	ds_read_b128 v[188:191], v154 offset:33792
	ds_read_b128 v[192:195], v154 offset:34816
	ds_read_b128 v[196:199], v154 offset:35840
	ds_read_b128 v[200:203], v154 offset:36864
	ds_read_b128 v[204:207], v154 offset:37888
	ds_read_b128 v[208:211], v154 offset:38912
	ds_read_b128 v[212:215], v154 offset:39936
	global_load_lds_dwordx4 v134, s[30:31]
	s_mov_b32 m0, s14
	s_nop 0
	global_load_lds_dwordx4 v136, s[30:31]
	s_barrier
	s_waitcnt lgkmcnt(0)
	s_waitcnt lgkmcnt(0)
	v_mfma_f32_16x16x32_bf16 v[126:129], v[130:133], v[184:187], v[126:129]
	v_mfma_f32_16x16x32_bf16 v[122:125], v[176:179], v[184:187], v[122:125]
	v_mfma_f32_16x16x32_bf16 v[118:121], v[130:133], v[192:195], v[118:121]
	v_mfma_f32_16x16x32_bf16 v[110:113], v[176:179], v[192:195], v[110:113]
	v_mfma_f32_16x16x32_bf16 v[98:101], v[130:133], v[200:203], v[98:101]
	v_mfma_f32_16x16x32_bf16 v[90:93], v[176:179], v[200:203], v[90:93]
	v_mfma_f32_16x16x32_bf16 v[86:89], v[130:133], v[208:211], v[86:89]
	v_mfma_f32_16x16x32_bf16 v[78:81], v[176:179], v[208:211], v[78:81]
	v_mfma_f32_16x16x32_bf16 v[126:129], v[146:149], v[188:191], v[126:129]
	v_mfma_f32_16x16x32_bf16 v[122:125], v[180:183], v[188:191], v[122:125]
	v_mfma_f32_16x16x32_bf16 v[118:121], v[146:149], v[196:199], v[118:121]
	v_mfma_f32_16x16x32_bf16 v[110:113], v[180:183], v[196:199], v[110:113]
	v_mfma_f32_16x16x32_bf16 v[98:101], v[146:149], v[204:207], v[98:101]
	v_mfma_f32_16x16x32_bf16 v[90:93], v[180:183], v[204:207], v[90:93]
	v_mfma_f32_16x16x32_bf16 v[86:89], v[146:149], v[212:215], v[86:89]
	v_mfma_f32_16x16x32_bf16 v[78:81], v[180:183], v[212:215], v[78:81]
	s_barrier
	s_mov_b32 m0, s15
	ds_read_b128 v[216:219], v171
	ds_read_b128 v[238:241], v172
	ds_read_b128 v[242:245], v173
	ds_read_b128 v[246:249], v174
	s_add_u32 s82, s28, 0x80
	s_addc_u32 s83, s29, 0
	global_load_lds_dwordx4 v0, s[82:83]
	s_mov_b32 m0, s16
	s_nop 0
	s_add_u32 s82, s28, 0x80
	s_addc_u32 s83, s29, 0
	global_load_lds_dwordx4 v138, s[82:83]
	s_barrier
	s_waitcnt lgkmcnt(0)
	s_waitcnt lgkmcnt(0)
	v_mfma_f32_16x16x32_bf16 v[114:117], v[216:219], v[184:187], v[114:117]
	v_mfma_f32_16x16x32_bf16 v[106:109], v[242:245], v[184:187], v[106:109]
	v_mfma_f32_16x16x32_bf16 v[102:105], v[216:219], v[192:195], v[102:105]
	v_mfma_f32_16x16x32_bf16 v[94:97], v[242:245], v[192:195], v[94:97]
	v_mfma_f32_16x16x32_bf16 v[82:85], v[216:219], v[200:203], v[82:85]
	v_mfma_f32_16x16x32_bf16 v[74:77], v[242:245], v[200:203], v[74:77]
	v_mfma_f32_16x16x32_bf16 v[70:73], v[216:219], v[208:211], v[70:73]
	v_mfma_f32_16x16x32_bf16 v[66:69], v[242:245], v[208:211], v[66:69]
	v_mfma_f32_16x16x32_bf16 v[114:117], v[238:241], v[188:191], v[114:117]
	v_mfma_f32_16x16x32_bf16 v[106:109], v[246:249], v[188:191], v[106:109]
	v_mfma_f32_16x16x32_bf16 v[102:105], v[238:241], v[196:199], v[102:105]
	v_mfma_f32_16x16x32_bf16 v[94:97], v[246:249], v[196:199], v[94:97]
	v_mfma_f32_16x16x32_bf16 v[82:85], v[238:241], v[204:207], v[82:85]
	v_mfma_f32_16x16x32_bf16 v[74:77], v[246:249], v[204:207], v[74:77]
	v_mfma_f32_16x16x32_bf16 v[70:73], v[238:241], v[212:215], v[70:73]
	v_mfma_f32_16x16x32_bf16 v[66:69], v[246:249], v[212:215], v[66:69]
	s_mov_b32 m0, s18
	s_barrier
; #define PG8_STAGE(bufoff, gbase, voff) do { _Pragma("unroll") for (int _i = 0; _i < 2; ++_i) \
;     __builtin_amdgcn_global_load_lds((const unsigned*)((const char*)(gbase) + (voff)[_i]), (PG8_LAS unsigned*)(lds + (bufoff) + ldsw + _i * 8192), 16, 0, 0); } while (0)
; #define PG8_LDA(dst, b, h) do { _Pragma("unroll") for (int m = 0; m < 4; ++m) _Pragma("unroll") for (int k = 0; k < 2; ++k) dst[m][k] = *(const PG8_LAS bf16x8*)(lds + PG8_SA(b, h) + aoff + m * 2048 + k * 1024); } while (0)
; #define PG8_MMA(ai, bj, At, Bt) do { __builtin_amdgcn_s_setprio(1); _Pragma("unroll") for (int m = 0; m < 4; ++m) _Pragma("unroll") for (int n = 0; n < 2; ++n) _Pragma("unroll") for (int k = 0; k < 2; ++k) \
;     acc[ai][bj][m][n] = __builtin_amdgcn_mfma_f32_16x16x32_bf16(Bt[n][k], At[m][k], acc[ai][bj][m][n], 0, 0, 0); __builtin_amdgcn_s_setprio(0); } while (0)
; #define PG8_WAIT_V(n) asm volatile("s_waitcnt vmcnt(" #n ")" ::: "memory")
; #define PG8_WAIT_L(n) asm volatile("s_waitcnt lgkmcnt(" #n ")" ::: "memory")
; #define PG8_BAR __builtin_amdgcn_s_barrier()
; #define PG8_SCHED __builtin_amdgcn_sched_barrier(0)
; #define PG8_RTAB_LOAD(var, unit) do { if constexpr (Epi::NEEDS_R) { var = *(const uint4*)(E.ssq + (size_t)((unit).pm * BM + (tid >> 1)) * 16 + (tid & 1) * 8); } } while (0)
; template <class Epi>
; DI void gemm_phase(const bf16_t* __restrict__ gA, const bf16_t* __restrict__ gBt, int M, int N, int K, const Epi& E, char* lds_generic) {
;     ...
;       PG8_LDA(At, 1, 1); PG8_STAGE(PG8_SA(1, 0), a3, voffA);
;       PG8_BAR; PG8_WAIT_L(0); PG8_MMA(1, 0, At, B0); PG8_BAR; PG8_SCHED;
;       PG8_STAGE(PG8_SB(1, 1), b3 + hstep, voffB);
;       PG8_WAIT_V(6); PG8_BAR; PG8_MMA(1, 1, At, B1); PG8_BAR;
;     }
;     uint4 rtn_ = {0u, 0u, 0u, 0u};
;     if (has_next) PG8_RTAB_LOAD(rtn_, nxt);
	ds_read_b128 v[184:187], v154 offset:49152
	ds_read_b128 v[188:191], v154 offset:50176
	ds_read_b128 v[192:195], v154 offset:51200
	ds_read_b128 v[196:199], v154 offset:52224
	ds_read_b128 v[200:203], v154 offset:53248
	ds_read_b128 v[204:207], v154 offset:54272
	ds_read_b128 v[208:211], v154 offset:55296
	ds_read_b128 v[212:215], v154 offset:56320
	s_add_u32 s82, s30, 0xfffc0080
	s_addc_u32 s83, s31, -1
	global_load_lds_dwordx4 v134, s[82:83]
	s_mov_b32 m0, s19
	s_nop 0
	s_add_u32 s82, s30, 0xfffc0080
	s_addc_u32 s83, s31, -1
	global_load_lds_dwordx4 v136, s[82:83]
	s_barrier
	s_waitcnt lgkmcnt(0)
	s_waitcnt lgkmcnt(0)
	v_mfma_f32_16x16x32_bf16 v[62:65], v[130:133], v[184:187], v[62:65]
	v_mfma_f32_16x16x32_bf16 v[58:61], v[176:179], v[184:187], v[58:61]
	v_mfma_f32_16x16x32_bf16 v[54:57], v[130:133], v[192:195], v[54:57]
	v_mfma_f32_16x16x32_bf16 v[46:49], v[176:179], v[192:195], v[46:49]
	v_mfma_f32_16x16x32_bf16 v[34:37], v[130:133], v[200:203], v[34:37]
	v_mfma_f32_16x16x32_bf16 v[26:29], v[176:179], v[200:203], v[26:29]
	v_mfma_f32_16x16x32_bf16 v[22:25], v[130:133], v[208:211], v[22:25]
	v_mfma_f32_16x16x32_bf16 v[14:17], v[176:179], v[208:211], v[14:17]
	v_mfma_f32_16x16x32_bf16 v[62:65], v[146:149], v[188:191], v[62:65]
	v_mfma_f32_16x16x32_bf16 v[58:61], v[180:183], v[188:191], v[58:61]
	v_mfma_f32_16x16x32_bf16 v[54:57], v[146:149], v[196:199], v[54:57]
	v_mfma_f32_16x16x32_bf16 v[46:49], v[180:183], v[196:199], v[46:49]
	v_mfma_f32_16x16x32_bf16 v[34:37], v[146:149], v[204:207], v[34:37]
	v_mfma_f32_16x16x32_bf16 v[26:29], v[180:183], v[204:207], v[26:29]
	v_mfma_f32_16x16x32_bf16 v[22:25], v[146:149], v[212:215], v[22:25]
	v_mfma_f32_16x16x32_bf16 v[14:17], v[180:183], v[212:215], v[14:17]
	s_barrier
	s_add_u32 s28, s28, 0x40080
	s_addc_u32 s29, s29, 0
	s_mov_b32 m0, s20
	s_nop 0
	global_load_lds_dwordx4 v0, s[28:29]
	s_mov_b32 m0, s21
	s_nop 0
	global_load_lds_dwordx4 v138, s[28:29]
	s_waitcnt vmcnt(6)
	s_barrier
	v_mfma_f32_16x16x32_bf16 v[50:53], v[216:219], v[184:187], v[50:53]
	v_mfma_f32_16x16x32_bf16 v[42:45], v[242:245], v[184:187], v[42:45]
	v_mfma_f32_16x16x32_bf16 v[38:41], v[216:219], v[192:195], v[38:41]
	v_mfma_f32_16x16x32_bf16 v[30:33], v[242:245], v[192:195], v[30:33]
	v_mfma_f32_16x16x32_bf16 v[18:21], v[216:219], v[200:203], v[18:21]
	v_mfma_f32_16x16x32_bf16 v[10:13], v[242:245], v[200:203], v[10:13]
	v_mfma_f32_16x16x32_bf16 v[6:9], v[216:219], v[208:211], v[6:9]
	v_mfma_f32_16x16x32_bf16 v[2:5], v[242:245], v[208:211], v[2:5]
	v_mfma_f32_16x16x32_bf16 v[50:53], v[238:241], v[188:191], v[50:53]
	v_mfma_f32_16x16x32_bf16 v[42:45], v[246:249], v[188:191], v[42:45]
	v_mfma_f32_16x16x32_bf16 v[38:41], v[238:241], v[196:199], v[38:41]
	v_mfma_f32_16x16x32_bf16 v[30:33], v[246:249], v[196:199], v[30:33]
	v_mfma_f32_16x16x32_bf16 v[18:21], v[238:241], v[204:207], v[18:21]
	v_mfma_f32_16x16x32_bf16 v[10:13], v[246:249], v[204:207], v[10:13]
	v_mfma_f32_16x16x32_bf16 v[6:9], v[238:241], v[212:215], v[6:9]
	v_mfma_f32_16x16x32_bf16 v[2:5], v[246:249], v[212:215], v[2:5]
	s_add_i32 s62, s62, 2
	s_add_u32 s80, s80, 0x100
	s_addc_u32 s81, s81, 0
	s_add_u32 s60, s60, 0x100
	s_addc_u32 s61, s61, 0
	s_cmp_gt_u32 s62, 13
	s_barrier
	s_cbranch_scc0 .LBB0_137
	v_mov_b32_e32 v130, 0
	s_and_b64 vcc, exec, s[38:39]
	v_mov_b32_e32 v131, 0
	v_mov_b32_e32 v132, 0
	v_mov_b32_e32 v133, 0
	s_cbranch_vccz .LBB0_140
	v_lshl_add_u32 v130, s26, 8, v150
	v_ashrrev_i32_e32 v131, 31, v130
	v_lshlrev_b64 v[130:131], 5, v[130:131]
	v_lshl_add_u64 v[130:131], v[140:141], 0, v[130:131]
	global_load_dwordx4 v[130:133], v[130:131], off

; #define PG8_STAGE(bufoff, gbase, voff) do { _Pragma("unroll") for (int _i = 0; _i < 2; ++_i) \
;     __builtin_amdgcn_global_load_lds((const unsigned*)((const char*)(gbase) + (voff)[_i]), (PG8_LAS unsigned*)(lds + (bufoff) + ldsw + _i * 8192), 16, 0, 0); } while (0)
; #define PG8_LDA(dst, b, h) do { _Pragma("unroll") for (int m = 0; m < 4; ++m) _Pragma("unroll") for (int k = 0; k < 2; ++k) dst[m][k] = *(const PG8_LAS bf16x8*)(lds + PG8_SA(b, h) + aoff + m * 2048 + k * 1024); } while (0)
; #define PG8_LDB(dst, b, h) do { _Pragma("unroll") for (int n = 0; n < 2; ++n) _Pragma("unroll") for (int k = 0; k < 2; ++k) dst[n][k] = *(const PG8_LAS bf16x8*)(lds + PG8_SB(b, h) + boff + n * 2048 + k * 1024); } while (0)
; #define PG8_MMA(ai, bj, At, Bt) do { __builtin_amdgcn_s_setprio(1); _Pragma("unroll") for (int m = 0; m < 4; ++m) _Pragma("unroll") for (int n = 0; n < 2; ++n) _Pragma("unroll") for (int k = 0; k < 2; ++k) \
;     acc[ai][bj][m][n] = __builtin_amdgcn_mfma_f32_16x16x32_bf16(Bt[n][k], At[m][k], acc[ai][bj][m][n], 0, 0, 0); __builtin_amdgcn_s_setprio(0); } while (0)
; #define PG8_WAIT_V(n) asm volatile("s_waitcnt vmcnt(" #n ")" ::: "memory")
; #define PG8_WAIT_L(n) asm volatile("s_waitcnt lgkmcnt(" #n ")" ::: "memory")
; #define PG8_BAR __builtin_amdgcn_s_barrier()
; #define PG8_SCHED __builtin_amdgcn_sched_barrier(0)
; template <class Epi>
; DI void gemm_phase(const bf16_t* __restrict__ gA, const bf16_t* __restrict__ gBt, int M, int N, int K, const Epi& E, char* lds_generic) {
;     ...
;       const bool last = (t == nt - 2);
;       const char* a1 = cA + (size_t)(t + 1) * kstep;
;       const char* a2 = last ? nA : cA + (size_t)(t + 2) * kstep; const char* b2 = last ? nB : cB + (size_t)(t + 2) * kstep;
;       const char* a3 = a2 + kstep; const char* b3 = b2 + kstep;
;       PG8_LDB(B0, 0, 0); PG8_SCHED; PG8_LDA(At, 0, 0); PG8_STAGE(PG8_SA(1, 1), a1 + hstep, voffA);
;       PG8_WAIT_L(8); PG8_BAR; PG8_WAIT_L(0); PG8_MMA(0, 0, At, B0); PG8_BAR; PG8_SCHED;
;       PG8_LDB(B1, 0, 1); PG8_STAGE(PG8_SB(0, 0), b2, voffB);
;       PG8_BAR; PG8_WAIT_L(0); PG8_MMA(0, 1, At, B1); PG8_BAR;
;       PG8_LDA(At, 0, 1); PG8_STAGE(PG8_SA(0, 0), a2, voffA);
;       PG8_BAR; PG8_WAIT_L(0); PG8_MMA(1, 0, At, B0); PG8_BAR; PG8_SCHED;
;       PG8_STAGE(PG8_SB(0, 1), b2 + hstep, voffB);
;       PG8_WAIT_V(6); PG8_BAR; PG8_MMA(1, 1, At, B1); PG8_BAR;
.LBB0_159:
	v_or_b32_e32 v130, 0x10000, v155
	v_add_u32_e32 v146, 0x10400, v155
	v_add_u32_e32 v158, 0x10800, v155
	ds_read_b128 v[130:133], v130
	ds_read_b128 v[146:149], v146
	v_add_u32_e32 v163, 0x10c00, v155
	ds_read_b128 v[158:161], v158
	ds_read_b128 v[166:169], v163
	s_add_u32 s23, s80, 0xfffc0080
	s_addc_u32 s24, s81, -1
	s_cmp_eq_u32 s22, 12
	s_cselect_b32 s31, s27, s24
	s_cselect_b32 s30, s58, s23
	s_cselect_b32 s29, s1, s61
	s_cselect_b32 s28, s59, s60
	s_add_i32 m0, s5, 0xc000
	ds_read_b128 v[170:173], v154
	ds_read_b128 v[174:177], v154 offset:1024
	ds_read_b128 v[178:181], v154 offset:2048
	ds_read_b128 v[182:185], v154 offset:3072
	ds_read_b128 v[186:189], v154 offset:4096
	ds_read_b128 v[190:193], v154 offset:5120
	ds_read_b128 v[194:197], v154 offset:6144
	ds_read_b128 v[198:201], v154 offset:7168
	global_load_lds_dwordx4 v142, s[80:81]
	s_add_i32 m0, s5, 0xe000
	s_nop 0
	global_load_lds_dwordx4 v144, s[80:81]
	s_barrier
	s_waitcnt lgkmcnt(0)
	s_waitcnt lgkmcnt(0)
	v_mfma_f32_16x16x32_bf16 v[126:129], v[130:133], v[170:173], v[126:129]
	v_mfma_f32_16x16x32_bf16 v[122:125], v[158:161], v[170:173], v[122:125]
	v_mfma_f32_16x16x32_bf16 v[118:121], v[130:133], v[178:181], v[118:121]
	v_mfma_f32_16x16x32_bf16 v[110:113], v[158:161], v[178:181], v[110:113]
	v_mfma_f32_16x16x32_bf16 v[98:101], v[130:133], v[186:189], v[98:101]
	v_mfma_f32_16x16x32_bf16 v[90:93], v[158:161], v[186:189], v[90:93]
	v_mfma_f32_16x16x32_bf16 v[86:89], v[130:133], v[194:197], v[86:89]
	v_mfma_f32_16x16x32_bf16 v[78:81], v[158:161], v[194:197], v[78:81]
	v_mfma_f32_16x16x32_bf16 v[126:129], v[146:149], v[174:177], v[126:129]
	v_mfma_f32_16x16x32_bf16 v[122:125], v[166:169], v[174:177], v[122:125]
	v_mfma_f32_16x16x32_bf16 v[118:121], v[146:149], v[182:185], v[118:121]
	v_mfma_f32_16x16x32_bf16 v[110:113], v[166:169], v[182:185], v[110:113]
	v_mfma_f32_16x16x32_bf16 v[98:101], v[146:149], v[190:193], v[98:101]
	v_mfma_f32_16x16x32_bf16 v[90:93], v[166:169], v[190:193], v[90:93]
	v_mfma_f32_16x16x32_bf16 v[86:89], v[146:149], v[198:201], v[86:89]
	v_mfma_f32_16x16x32_bf16 v[78:81], v[166:169], v[198:201], v[78:81]
	s_barrier
	v_or_b32_e32 v163, 0x14000, v155
	s_mov_b32 m0, s6
	v_add_u32_e32 v165, 0x14400, v155
	ds_read_b128 v[202:205], v163
	ds_read_b128 v[206:209], v165
	v_add_u32_e32 v163, 0x14800, v155
	v_add_u32_e32 v165, 0x14c00, v155
	ds_read_b128 v[210:213], v163
	ds_read_b128 v[214:217], v165
	global_load_lds_dwordx4 v0, s[28:29]
	s_mov_b32 m0, s7
	s_nop 0
	global_load_lds_dwordx4 v138, s[28:29]
	s_barrier
	s_waitcnt lgkmcnt(0)
	s_waitcnt lgkmcnt(0)
	v_mfma_f32_16x16x32_bf16 v[114:117], v[202:205], v[170:173], v[114:117]
	v_mfma_f32_16x16x32_bf16 v[106:109], v[210:213], v[170:173], v[106:109]
	v_mfma_f32_16x16x32_bf16 v[102:105], v[202:205], v[178:181], v[102:105]
	v_mfma_f32_16x16x32_bf16 v[94:97], v[210:213], v[178:181], v[94:97]
	v_mfma_f32_16x16x32_bf16 v[82:85], v[202:205], v[186:189], v[82:85]
	v_mfma_f32_16x16x32_bf16 v[74:77], v[210:213], v[186:189], v[74:77]
	v_mfma_f32_16x16x32_bf16 v[70:73], v[202:205], v[194:197], v[70:73]
	v_mfma_f32_16x16x32_bf16 v[66:69], v[210:213], v[194:197], v[66:69]
	v_mfma_f32_16x16x32_bf16 v[114:117], v[206:209], v[174:177], v[114:117]
	v_mfma_f32_16x16x32_bf16 v[106:109], v[214:217], v[174:177], v[106:109]
	v_mfma_f32_16x16x32_bf16 v[102:105], v[206:209], v[182:185], v[102:105]
	v_mfma_f32_16x16x32_bf16 v[94:97], v[214:217], v[182:185], v[94:97]
	v_mfma_f32_16x16x32_bf16 v[82:85], v[206:209], v[190:193], v[82:85]
	v_mfma_f32_16x16x32_bf16 v[74:77], v[214:217], v[190:193], v[74:77]
	v_mfma_f32_16x16x32_bf16 v[70:73], v[206:209], v[198:201], v[70:73]
	v_mfma_f32_16x16x32_bf16 v[66:69], v[214:217], v[198:201], v[66:69]
	s_mov_b32 m0, s5
	s_barrier
	ds_read_b128 v[170:173], v154 offset:16384
	ds_read_b128 v[174:177], v154 offset:17408
	ds_read_b128 v[178:181], v154 offset:18432
	ds_read_b128 v[182:185], v154 offset:19456
	ds_read_b128 v[186:189], v154 offset:20480
	ds_read_b128 v[190:193], v154 offset:21504
	ds_read_b128 v[194:197], v154 offset:22528
	ds_read_b128 v[198:201], v154 offset:23552
	global_load_lds_dwordx4 v134, s[30:31]
	s_mov_b32 m0, s8
	s_nop 0
	global_load_lds_dwordx4 v136, s[30:31]
	s_barrier
	s_waitcnt lgkmcnt(0)
	s_waitcnt lgkmcnt(0)
	v_mfma_f32_16x16x32_bf16 v[62:65], v[130:133], v[170:173], v[62:65]
	v_mfma_f32_16x16x32_bf16 v[58:61], v[158:161], v[170:173], v[58:61]
	v_mfma_f32_16x16x32_bf16 v[54:57], v[130:133], v[178:181], v[54:57]
	v_mfma_f32_16x16x32_bf16 v[46:49], v[158:161], v[178:181], v[46:49]
	v_mfma_f32_16x16x32_bf16 v[34:37], v[130:133], v[186:189], v[34:37]
	v_mfma_f32_16x16x32_bf16 v[26:29], v[158:161], v[186:189], v[26:29]
	v_mfma_f32_16x16x32_bf16 v[22:25], v[130:133], v[194:197], v[22:25]
	v_mfma_f32_16x16x32_bf16 v[14:17], v[158:161], v[194:197], v[14:17]
	v_mfma_f32_16x16x32_bf16 v[62:65], v[146:149], v[174:177], v[62:65]
	v_mfma_f32_16x16x32_bf16 v[58:61], v[166:169], v[174:177], v[58:61]
	v_mfma_f32_16x16x32_bf16 v[54:57], v[146:149], v[182:185], v[54:57]
	v_mfma_f32_16x16x32_bf16 v[46:49], v[166:169], v[182:185], v[46:49]
	v_mfma_f32_16x16x32_bf16 v[34:37], v[146:149], v[190:193], v[34:37]
	v_mfma_f32_16x16x32_bf16 v[26:29], v[166:169], v[190:193], v[26:29]
	v_mfma_f32_16x16x32_bf16 v[22:25], v[146:149], v[198:201], v[22:25]
	v_mfma_f32_16x16x32_bf16 v[14:17], v[166:169], v[198:201], v[14:17]
	s_barrier
	s_add_u32 s82, s28, 0x40000
	s_addc_u32 s83, s29, 0
	s_mov_b32 m0, s9
	s_nop 0
	global_load_lds_dwordx4 v0, s[82:83]
	s_mov_b32 m0, s12
	s_nop 0
	global_load_lds_dwordx4 v138, s[82:83]
	s_waitcnt vmcnt(6)
	s_barrier
; #define PG8_STAGE(bufoff, gbase, voff) do { _Pragma("unroll") for (int _i = 0; _i < 2; ++_i) \
;     __builtin_amdgcn_global_load_lds((const unsigned*)((const char*)(gbase) + (voff)[_i]), (PG8_LAS unsigned*)(lds + (bufoff) + ldsw + _i * 8192), 16, 0, 0); } while (0)
; #define PG8_LDA(dst, b, h) do { _Pragma("unroll") for (int m = 0; m < 4; ++m) _Pragma("unroll") for (int k = 0; k < 2; ++k) dst[m][k] = *(const PG8_LAS bf16x8*)(lds + PG8_SA(b, h) + aoff + m * 2048 + k * 1024); } while (0)
; #define PG8_LDB(dst, b, h) do { _Pragma("unroll") for (int n = 0; n < 2; ++n) _Pragma("unroll") for (int k = 0; k < 2; ++k) dst[n][k] = *(const PG8_LAS bf16x8*)(lds + PG8_SB(b, h) + boff + n * 2048 + k * 1024); } while (0)
; #define PG8_MMA(ai, bj, At, Bt) do { __builtin_amdgcn_s_setprio(1); _Pragma("unroll") for (int m = 0; m < 4; ++m) _Pragma("unroll") for (int n = 0; n < 2; ++n) _Pragma("unroll") for (int k = 0; k < 2; ++k) \
;     acc[ai][bj][m][n] = __builtin_amdgcn_mfma_f32_16x16x32_bf16(Bt[n][k], At[m][k], acc[ai][bj][m][n], 0, 0, 0); __builtin_amdgcn_s_setprio(0); } while (0)
; #define PG8_WAIT_V(n) asm volatile("s_waitcnt vmcnt(" #n ")" ::: "memory")
; #define PG8_WAIT_L(n) asm volatile("s_waitcnt lgkmcnt(" #n ")" ::: "memory")
; #define PG8_BAR __builtin_amdgcn_s_barrier()
; #define PG8_SCHED __builtin_amdgcn_sched_barrier(0)
; template <class Epi>
; DI void gemm_phase(const bf16_t* __restrict__ gA, const bf16_t* __restrict__ gBt, int M, int N, int K, const Epi& E, char* lds_generic) {
;     ...
;       PG8_WAIT_V(6); PG8_BAR; PG8_MMA(1, 1, At, B1); PG8_BAR;
;       PG8_LDB(B0, 1, 0); PG8_SCHED; PG8_LDA(At, 1, 0); PG8_STAGE(PG8_SA(0, 1), a2 + hstep, voffA);
;       PG8_WAIT_L(8); PG8_BAR; PG8_WAIT_L(0); PG8_MMA(0, 0, At, B0); PG8_BAR; PG8_SCHED;
;       PG8_LDB(B1, 1, 1); PG8_STAGE(PG8_SB(1, 0), b3, voffB);
;       PG8_BAR; PG8_WAIT_L(0); PG8_MMA(0, 1, At, B1); PG8_BAR;
;       PG8_LDA(At, 1, 1); PG8_STAGE(PG8_SA(1, 0), a3, voffA);
	v_mfma_f32_16x16x32_bf16 v[50:53], v[202:205], v[170:173], v[50:53]
	v_mfma_f32_16x16x32_bf16 v[42:45], v[210:213], v[170:173], v[42:45]
	v_mfma_f32_16x16x32_bf16 v[38:41], v[202:205], v[178:181], v[38:41]
	v_mfma_f32_16x16x32_bf16 v[30:33], v[210:213], v[178:181], v[30:33]
	v_mfma_f32_16x16x32_bf16 v[18:21], v[202:205], v[186:189], v[18:21]
	v_mfma_f32_16x16x32_bf16 v[10:13], v[210:213], v[186:189], v[10:13]
	v_mfma_f32_16x16x32_bf16 v[6:9], v[202:205], v[194:197], v[6:9]
	v_mfma_f32_16x16x32_bf16 v[2:5], v[210:213], v[194:197], v[2:5]
	v_mfma_f32_16x16x32_bf16 v[50:53], v[206:209], v[174:177], v[50:53]
	v_mfma_f32_16x16x32_bf16 v[42:45], v[214:217], v[174:177], v[42:45]
	v_mfma_f32_16x16x32_bf16 v[38:41], v[206:209], v[182:185], v[38:41]
	v_mfma_f32_16x16x32_bf16 v[30:33], v[214:217], v[182:185], v[30:33]
	v_mfma_f32_16x16x32_bf16 v[18:21], v[206:209], v[190:193], v[18:21]
	v_mfma_f32_16x16x32_bf16 v[10:13], v[214:217], v[190:193], v[10:13]
	v_mfma_f32_16x16x32_bf16 v[6:9], v[206:209], v[198:201], v[6:9]
	v_mfma_f32_16x16x32_bf16 v[2:5], v[214:217], v[198:201], v[2:5]
	v_or_b32_e32 v130, 0x18000, v155
	v_add_u32_e32 v146, 0x18400, v155
	v_add_u32_e32 v158, 0x18800, v155
	s_barrier
	ds_read_b128 v[130:133], v130
	ds_read_b128 v[146:149], v146
	v_add_u32_e32 v163, 0x18c00, v155
	ds_read_b128 v[158:161], v158
	ds_read_b128 v[166:169], v163
	s_add_u32 s30, s30, 0x40000
	s_addc_u32 s31, s31, 0
	s_mov_b32 m0, s13
	ds_read_b128 v[170:173], v154 offset:32768
	ds_read_b128 v[174:177], v154 offset:33792
	ds_read_b128 v[178:181], v154 offset:34816
	ds_read_b128 v[182:185], v154 offset:35840
	ds_read_b128 v[186:189], v154 offset:36864
	ds_read_b128 v[190:193], v154 offset:37888
	ds_read_b128 v[194:197], v154 offset:38912
	ds_read_b128 v[198:201], v154 offset:39936
	global_load_lds_dwordx4 v134, s[30:31]
	s_mov_b32 m0, s14
	s_nop 0
	global_load_lds_dwordx4 v136, s[30:31]
	s_barrier
	s_waitcnt lgkmcnt(0)
	s_waitcnt lgkmcnt(0)
	v_mfma_f32_16x16x32_bf16 v[126:129], v[130:133], v[170:173], v[126:129]
	v_mfma_f32_16x16x32_bf16 v[122:125], v[158:161], v[170:173], v[122:125]
	v_mfma_f32_16x16x32_bf16 v[118:121], v[130:133], v[178:181], v[118:121]
	v_mfma_f32_16x16x32_bf16 v[110:113], v[158:161], v[178:181], v[110:113]
	v_mfma_f32_16x16x32_bf16 v[98:101], v[130:133], v[186:189], v[98:101]
	v_mfma_f32_16x16x32_bf16 v[90:93], v[158:161], v[186:189], v[90:93]
	v_mfma_f32_16x16x32_bf16 v[86:89], v[130:133], v[194:197], v[86:89]
	v_mfma_f32_16x16x32_bf16 v[78:81], v[158:161], v[194:197], v[78:81]
	v_mfma_f32_16x16x32_bf16 v[126:129], v[146:149], v[174:177], v[126:129]
	v_mfma_f32_16x16x32_bf16 v[122:125], v[166:169], v[174:177], v[122:125]
	v_mfma_f32_16x16x32_bf16 v[118:121], v[146:149], v[182:185], v[118:121]
	v_mfma_f32_16x16x32_bf16 v[110:113], v[166:169], v[182:185], v[110:113]
	v_mfma_f32_16x16x32_bf16 v[98:101], v[146:149], v[190:193], v[98:101]
	v_mfma_f32_16x16x32_bf16 v[90:93], v[166:169], v[190:193], v[90:93]
	v_mfma_f32_16x16x32_bf16 v[86:89], v[146:149], v[198:201], v[86:89]
	v_mfma_f32_16x16x32_bf16 v[78:81], v[166:169], v[198:201], v[78:81]
	s_barrier
	v_or_b32_e32 v163, 0x1c000, v155
	s_mov_b32 m0, s15
	v_add_u32_e32 v165, 0x1c400, v155
	ds_read_b128 v[202:205], v163
	ds_read_b128 v[206:209], v165
	v_add_u32_e32 v163, 0x1c800, v155
	v_add_u32_e32 v165, 0x1cc00, v155
	ds_read_b128 v[210:213], v163
	ds_read_b128 v[214:217], v165
	s_add_u32 s82, s28, 0x80
	s_addc_u32 s83, s29, 0
	global_load_lds_dwordx4 v0, s[82:83]
	s_mov_b32 m0, s16
	s_nop 0
	s_add_u32 s82, s28, 0x80
	s_addc_u32 s83, s29, 0
	global_load_lds_dwordx4 v138, s[82:83]
	s_barrier
; #define PG8_STAGE(bufoff, gbase, voff) do { _Pragma("unroll") for (int _i = 0; _i < 2; ++_i) \
;     __builtin_amdgcn_global_load_lds((const unsigned*)((const char*)(gbase) + (voff)[_i]), (PG8_LAS unsigned*)(lds + (bufoff) + ldsw + _i * 8192), 16, 0, 0); } while (0)
; #define PG8_LDA(dst, b, h) do { _Pragma("unroll") for (int m = 0; m < 4; ++m) _Pragma("unroll") for (int k = 0; k < 2; ++k) dst[m][k] = *(const PG8_LAS bf16x8*)(lds + PG8_SA(b, h) + aoff + m * 2048 + k * 1024); } while (0)
; #define PG8_MMA(ai, bj, At, Bt) do { __builtin_amdgcn_s_setprio(1); _Pragma("unroll") for (int m = 0; m < 4; ++m) _Pragma("unroll") for (int n = 0; n < 2; ++n) _Pragma("unroll") for (int k = 0; k < 2; ++k) \
;     acc[ai][bj][m][n] = __builtin_amdgcn_mfma_f32_16x16x32_bf16(Bt[n][k], At[m][k], acc[ai][bj][m][n], 0, 0, 0); __builtin_amdgcn_s_setprio(0); } while (0)
; #define PG8_WAIT_V(n) asm volatile("s_waitcnt vmcnt(" #n ")" ::: "memory")
; #define PG8_WAIT_L(n) asm volatile("s_waitcnt lgkmcnt(" #n ")" ::: "memory")
; #define PG8_BAR __builtin_amdgcn_s_barrier()
; #define PG8_SCHED __builtin_amdgcn_sched_barrier(0)
; #define PG8_RTAB_LOAD(var, unit) do { if constexpr (Epi::NEEDS_R) { var = *(const uint4*)(E.ssq + (size_t)((unit).pm * BM + (tid >> 1)) * 16 + (tid & 1) * 8); } } while (0)
; template <class Epi>
; DI void gemm_phase(const bf16_t* __restrict__ gA, const bf16_t* __restrict__ gBt, int M, int N, int K, const Epi& E, char* lds_generic) {
;     ...
;       PG8_LDA(At, 1, 1); PG8_STAGE(PG8_SA(1, 0), a3, voffA);
;       PG8_BAR; PG8_WAIT_L(0); PG8_MMA(1, 0, At, B0); PG8_BAR; PG8_SCHED;
;       PG8_STAGE(PG8_SB(1, 1), b3 + hstep, voffB);
;       PG8_WAIT_V(6); PG8_BAR; PG8_MMA(1, 1, At, B1); PG8_BAR;
;     }
;     uint4 rtn_ = {0u, 0u, 0u, 0u};
;     if (has_next) PG8_RTAB_LOAD(rtn_, nxt);
	s_waitcnt lgkmcnt(0)
	s_waitcnt lgkmcnt(0)
	v_mfma_f32_16x16x32_bf16 v[114:117], v[202:205], v[170:173], v[114:117]
	v_mfma_f32_16x16x32_bf16 v[106:109], v[210:213], v[170:173], v[106:109]
	v_mfma_f32_16x16x32_bf16 v[102:105], v[202:205], v[178:181], v[102:105]
	v_mfma_f32_16x16x32_bf16 v[94:97], v[210:213], v[178:181], v[94:97]
	v_mfma_f32_16x16x32_bf16 v[82:85], v[202:205], v[186:189], v[82:85]
	v_mfma_f32_16x16x32_bf16 v[74:77], v[210:213], v[186:189], v[74:77]
	v_mfma_f32_16x16x32_bf16 v[70:73], v[202:205], v[194:197], v[70:73]
	v_mfma_f32_16x16x32_bf16 v[66:69], v[210:213], v[194:197], v[66:69]
	v_mfma_f32_16x16x32_bf16 v[114:117], v[206:209], v[174:177], v[114:117]
	v_mfma_f32_16x16x32_bf16 v[106:109], v[214:217], v[174:177], v[106:109]
	v_mfma_f32_16x16x32_bf16 v[102:105], v[206:209], v[182:185], v[102:105]
	v_mfma_f32_16x16x32_bf16 v[94:97], v[214:217], v[182:185], v[94:97]
	v_mfma_f32_16x16x32_bf16 v[82:85], v[206:209], v[190:193], v[82:85]
	v_mfma_f32_16x16x32_bf16 v[74:77], v[214:217], v[190:193], v[74:77]
	v_mfma_f32_16x16x32_bf16 v[70:73], v[206:209], v[198:201], v[70:73]
	v_mfma_f32_16x16x32_bf16 v[66:69], v[214:217], v[198:201], v[66:69]
	s_mov_b32 m0, s18
	s_barrier
	ds_read_b128 v[170:173], v154 offset:49152
	ds_read_b128 v[174:177], v154 offset:50176
	ds_read_b128 v[178:181], v154 offset:51200
	ds_read_b128 v[182:185], v154 offset:52224
	ds_read_b128 v[186:189], v154 offset:53248
	ds_read_b128 v[190:193], v154 offset:54272
	ds_read_b128 v[194:197], v154 offset:55296
	ds_read_b128 v[198:201], v154 offset:56320
	s_add_u32 s82, s30, 0xfffc0080
	s_addc_u32 s83, s31, -1
	global_load_lds_dwordx4 v134, s[82:83]
	s_mov_b32 m0, s19
	s_nop 0
	s_add_u32 s82, s30, 0xfffc0080
	s_addc_u32 s83, s31, -1
	global_load_lds_dwordx4 v136, s[82:83]
	s_barrier
	s_waitcnt lgkmcnt(0)
	s_waitcnt lgkmcnt(0)
	v_mfma_f32_16x16x32_bf16 v[62:65], v[130:133], v[170:173], v[62:65]
	v_mfma_f32_16x16x32_bf16 v[58:61], v[158:161], v[170:173], v[58:61]
	v_mfma_f32_16x16x32_bf16 v[54:57], v[130:133], v[178:181], v[54:57]
	v_mfma_f32_16x16x32_bf16 v[46:49], v[158:161], v[178:181], v[46:49]
	v_mfma_f32_16x16x32_bf16 v[34:37], v[130:133], v[186:189], v[34:37]
	v_mfma_f32_16x16x32_bf16 v[26:29], v[158:161], v[186:189], v[26:29]
	v_mfma_f32_16x16x32_bf16 v[22:25], v[130:133], v[194:197], v[22:25]
	v_mfma_f32_16x16x32_bf16 v[14:17], v[158:161], v[194:197], v[14:17]
	v_mfma_f32_16x16x32_bf16 v[62:65], v[146:149], v[174:177], v[62:65]
	v_mfma_f32_16x16x32_bf16 v[58:61], v[166:169], v[174:177], v[58:61]
	v_mfma_f32_16x16x32_bf16 v[54:57], v[146:149], v[182:185], v[54:57]
	v_mfma_f32_16x16x32_bf16 v[46:49], v[166:169], v[182:185], v[46:49]
	v_mfma_f32_16x16x32_bf16 v[34:37], v[146:149], v[190:193], v[34:37]
	v_mfma_f32_16x16x32_bf16 v[26:29], v[166:169], v[190:193], v[26:29]
	v_mfma_f32_16x16x32_bf16 v[22:25], v[146:149], v[198:201], v[22:25]
	v_mfma_f32_16x16x32_bf16 v[14:17], v[166:169], v[198:201], v[14:17]
	s_barrier
	s_add_u32 s28, s28, 0x40080
	s_addc_u32 s29, s29, 0
	s_mov_b32 m0, s20
	s_nop 0
	global_load_lds_dwordx4 v0, s[28:29]
	s_mov_b32 m0, s21
	s_nop 0
	global_load_lds_dwordx4 v138, s[28:29]
	s_waitcnt vmcnt(6)
	s_barrier
	v_mfma_f32_16x16x32_bf16 v[50:53], v[202:205], v[170:173], v[50:53]
	v_mfma_f32_16x16x32_bf16 v[42:45], v[210:213], v[170:173], v[42:45]
	v_mfma_f32_16x16x32_bf16 v[38:41], v[202:205], v[178:181], v[38:41]
	v_mfma_f32_16x16x32_bf16 v[30:33], v[210:213], v[178:181], v[30:33]
	v_mfma_f32_16x16x32_bf16 v[18:21], v[202:205], v[186:189], v[18:21]
	v_mfma_f32_16x16x32_bf16 v[10:13], v[210:213], v[186:189], v[10:13]
	v_mfma_f32_16x16x32_bf16 v[6:9], v[202:205], v[194:197], v[6:9]
	v_mfma_f32_16x16x32_bf16 v[2:5], v[210:213], v[194:197], v[2:5]
	v_mfma_f32_16x16x32_bf16 v[50:53], v[206:209], v[174:177], v[50:53]
	v_mfma_f32_16x16x32_bf16 v[42:45], v[214:217], v[174:177], v[42:45]
	v_mfma_f32_16x16x32_bf16 v[38:41], v[206:209], v[182:185], v[38:41]
	v_mfma_f32_16x16x32_bf16 v[30:33], v[214:217], v[182:185], v[30:33]
	v_mfma_f32_16x16x32_bf16 v[18:21], v[206:209], v[190:193], v[18:21]
	v_mfma_f32_16x16x32_bf16 v[10:13], v[214:217], v[190:193], v[10:13]
	v_mfma_f32_16x16x32_bf16 v[6:9], v[206:209], v[198:201], v[6:9]
	v_mfma_f32_16x16x32_bf16 v[2:5], v[214:217], v[198:201], v[2:5]
	s_add_i32 s22, s22, 2
	s_add_u32 s80, s80, 0x100
	s_addc_u32 s81, s81, 0
	s_add_u32 s60, s60, 0x100
	s_addc_u32 s61, s61, 0
	s_cmp_gt_u32 s22, 13
	s_barrier
	s_cbranch_scc0 .LBB0_159
	v_mov_b32_e32 v130, 0
	s_and_b64 vcc, exec, s[38:39]
	v_mov_b32_e32 v131, 0
	v_mov_b32_e32 v132, 0
	v_mov_b32_e32 v133, 0
	s_cbranch_vccz .LBB0_162
	v_lshl_add_u32 v130, s26, 8, v150
	v_ashrrev_i32_e32 v131, 31, v130
	v_lshlrev_b64 v[130:131], 5, v[130:131]
	v_lshl_add_u64 v[130:131], v[140:141], 0, v[130:131]
	global_load_dwordx4 v[130:133], v[130:131], off

; #define PG8_STAGE(bufoff, gbase, voff) do { _Pragma("unroll") for (int _i = 0; _i < 2; ++_i) \
;     __builtin_amdgcn_global_load_lds((const unsigned*)((const char*)(gbase) + (voff)[_i]), (PG8_LAS unsigned*)(lds + (bufoff) + ldsw + _i * 8192), 16, 0, 0); } while (0)
; #define PG8_LDA(dst, b, h) do { _Pragma("unroll") for (int m = 0; m < 4; ++m) _Pragma("unroll") for (int k = 0; k < 2; ++k) dst[m][k] = *(const PG8_LAS bf16x8*)(lds + PG8_SA(b, h) + aoff + m * 2048 + k * 1024); } while (0)
; #define PG8_LDB(dst, b, h) do { _Pragma("unroll") for (int n = 0; n < 2; ++n) _Pragma("unroll") for (int k = 0; k < 2; ++k) dst[n][k] = *(const PG8_LAS bf16x8*)(lds + PG8_SB(b, h) + boff + n * 2048 + k * 1024); } while (0)
; #define PG8_MMA(ai, bj, At, Bt) do { __builtin_amdgcn_s_setprio(1); _Pragma("unroll") for (int m = 0; m < 4; ++m) _Pragma("unroll") for (int n = 0; n < 2; ++n) _Pragma("unroll") for (int k = 0; k < 2; ++k) \
;     acc[ai][bj][m][n] = __builtin_amdgcn_mfma_f32_16x16x32_bf16(Bt[n][k], At[m][k], acc[ai][bj][m][n], 0, 0, 0); __builtin_amdgcn_s_setprio(0); } while (0)
; #define PG8_WAIT_V(n) asm volatile("s_waitcnt vmcnt(" #n ")" ::: "memory")
; #define PG8_WAIT_L(n) asm volatile("s_waitcnt lgkmcnt(" #n ")" ::: "memory")
; #define PG8_BAR __builtin_amdgcn_s_barrier()
; #define PG8_SCHED __builtin_amdgcn_sched_barrier(0)
; template <class Epi>
; DI void gemm_phase(const bf16_t* __restrict__ gA, const bf16_t* __restrict__ gBt, int M, int N, int K, const Epi& E, char* lds_generic) {
;     ...
;       const bool last = (t == nt - 2);
;       const char* a1 = cA + (size_t)(t + 1) * kstep;
;       const char* a2 = last ? nA : cA + (size_t)(t + 2) * kstep; const char* b2 = last ? nB : cB + (size_t)(t + 2) * kstep;
;       const char* a3 = a2 + kstep; const char* b3 = b2 + kstep;
;       PG8_LDB(B0, 0, 0); PG8_SCHED; PG8_LDA(At, 0, 0); PG8_STAGE(PG8_SA(1, 1), a1 + hstep, voffA);
;       PG8_WAIT_L(8); PG8_BAR; PG8_WAIT_L(0); PG8_MMA(0, 0, At, B0); PG8_BAR; PG8_SCHED;
;       PG8_LDB(B1, 0, 1); PG8_STAGE(PG8_SB(0, 0), b2, voffB);
;       PG8_BAR; PG8_WAIT_L(0); PG8_MMA(0, 1, At, B1); PG8_BAR;
;       PG8_LDA(At, 0, 1); PG8_STAGE(PG8_SA(0, 0), a2, voffA);
;       PG8_BAR; PG8_WAIT_L(0); PG8_MMA(1, 0, At, B0); PG8_BAR; PG8_SCHED;
;       PG8_STAGE(PG8_SB(0, 1), b2 + hstep, voffB);
;       PG8_WAIT_V(6); PG8_BAR; PG8_MMA(1, 1, At, B1); PG8_BAR;
.LBB0_511:
	v_or_b32_e32 v140, 0x10000, v146
	v_add_u32_e32 v148, 0x10400, v146
	v_add_u32_e32 v152, 0x10800, v146
	v_add_u32_e32 v156, 0x10c00, v146
	ds_read_b128 v[140:143], v140
	ds_read_b128 v[148:151], v148
	ds_read_b128 v[152:155], v152
	ds_read_b128 v[156:159], v156
	s_add_u32 s0, s28, 0xfffc0080
	s_addc_u32 s1, s29, -1
	s_cmp_eq_u32 s60, 12
	s_cselect_b32 s31, s22, s1
	s_cselect_b32 s30, s23, s0
	s_cselect_b32 s1, s27, s59
	s_cselect_b32 s0, s39, s58
	s_add_i32 m0, s6, 0xc000
	ds_read_b128 v[166:169], v145
	ds_read_b128 v[170:173], v145 offset:1024
	ds_read_b128 v[174:177], v145 offset:2048
	ds_read_b128 v[178:181], v145 offset:3072
	ds_read_b128 v[182:185], v145 offset:4096
	ds_read_b128 v[186:189], v145 offset:5120
	ds_read_b128 v[190:193], v145 offset:6144
	ds_read_b128 v[194:197], v145 offset:7168
	global_load_lds_dwordx4 v136, s[28:29]
	s_add_i32 m0, s6, 0xe000
	s_nop 0
	global_load_lds_dwordx4 v138, s[28:29]
	s_barrier
	s_waitcnt lgkmcnt(0)
	s_waitcnt lgkmcnt(0)
	v_mfma_f32_16x16x32_bf16 v[118:121], v[140:143], v[166:169], v[118:121]
	v_mfma_f32_16x16x32_bf16 v[110:113], v[152:155], v[166:169], v[110:113]
	v_mfma_f32_16x16x32_bf16 v[90:93], v[140:143], v[174:177], v[90:93]
	v_mfma_f32_16x16x32_bf16 v[82:85], v[152:155], v[174:177], v[82:85]
	v_mfma_f32_16x16x32_bf16 v[62:65], v[140:143], v[182:185], v[62:65]
	v_mfma_f32_16x16x32_bf16 v[50:53], v[152:155], v[182:185], v[50:53]
	v_mfma_f32_16x16x32_bf16 v[42:45], v[140:143], v[190:193], v[42:45]
	v_mfma_f32_16x16x32_bf16 v[22:25], v[152:155], v[190:193], v[22:25]
	v_mfma_f32_16x16x32_bf16 v[118:121], v[148:151], v[170:173], v[118:121]
	v_mfma_f32_16x16x32_bf16 v[110:113], v[156:159], v[170:173], v[110:113]
	v_mfma_f32_16x16x32_bf16 v[90:93], v[148:151], v[178:181], v[90:93]
	v_mfma_f32_16x16x32_bf16 v[82:85], v[156:159], v[178:181], v[82:85]
	v_mfma_f32_16x16x32_bf16 v[62:65], v[148:151], v[186:189], v[62:65]
	v_mfma_f32_16x16x32_bf16 v[50:53], v[156:159], v[186:189], v[50:53]
	v_mfma_f32_16x16x32_bf16 v[42:45], v[148:151], v[194:197], v[42:45]
	v_mfma_f32_16x16x32_bf16 v[22:25], v[156:159], v[194:197], v[22:25]
	s_barrier
	v_or_b32_e32 v160, 0x14000, v146
	v_add_u32_e32 v161, 0x14400, v146
	ds_read_b128 v[198:201], v160
	ds_read_b128 v[202:205], v161
	v_add_u32_e32 v160, 0x14800, v146
	v_add_u32_e32 v161, 0x14c00, v146
	s_mov_b32 m0, s7
	ds_read_b128 v[206:209], v160
	ds_read_b128 v[210:213], v161
	global_load_lds_dwordx4 v0, s[0:1]
	s_mov_b32 m0, s12
	s_nop 0
	global_load_lds_dwordx4 v130, s[0:1]
	s_barrier
	s_waitcnt lgkmcnt(0)
	s_waitcnt lgkmcnt(0)
	v_mfma_f32_16x16x32_bf16 v[122:125], v[198:201], v[166:169], v[122:125]
	v_mfma_f32_16x16x32_bf16 v[126:129], v[206:209], v[166:169], v[126:129]
	v_mfma_f32_16x16x32_bf16 v[102:105], v[198:201], v[174:177], v[102:105]
	v_mfma_f32_16x16x32_bf16 v[114:117], v[206:209], v[174:177], v[114:117]
	v_mfma_f32_16x16x32_bf16 v[86:89], v[198:201], v[182:185], v[86:89]
	v_mfma_f32_16x16x32_bf16 v[98:101], v[206:209], v[182:185], v[98:101]
	v_mfma_f32_16x16x32_bf16 v[58:61], v[198:201], v[190:193], v[58:61]
	v_mfma_f32_16x16x32_bf16 v[74:77], v[206:209], v[190:193], v[74:77]
	v_mfma_f32_16x16x32_bf16 v[122:125], v[202:205], v[170:173], v[122:125]
	v_mfma_f32_16x16x32_bf16 v[126:129], v[210:213], v[170:173], v[126:129]
	v_mfma_f32_16x16x32_bf16 v[102:105], v[202:205], v[178:181], v[102:105]
	v_mfma_f32_16x16x32_bf16 v[114:117], v[210:213], v[178:181], v[114:117]
	v_mfma_f32_16x16x32_bf16 v[86:89], v[202:205], v[186:189], v[86:89]
	v_mfma_f32_16x16x32_bf16 v[98:101], v[210:213], v[186:189], v[98:101]
	v_mfma_f32_16x16x32_bf16 v[58:61], v[202:205], v[194:197], v[58:61]
	v_mfma_f32_16x16x32_bf16 v[74:77], v[210:213], v[194:197], v[74:77]
	s_mov_b32 m0, s6
	s_barrier
	ds_read_b128 v[166:169], v145 offset:16384
	ds_read_b128 v[170:173], v145 offset:17408
	ds_read_b128 v[174:177], v145 offset:18432
	ds_read_b128 v[178:181], v145 offset:19456
	ds_read_b128 v[182:185], v145 offset:20480
	ds_read_b128 v[186:189], v145 offset:21504
	ds_read_b128 v[190:193], v145 offset:22528
	ds_read_b128 v[194:197], v145 offset:23552
	global_load_lds_dwordx4 v134, s[30:31]
	s_mov_b32 m0, s13
	s_nop 0
	global_load_lds_dwordx4 v132, s[30:31]
	s_barrier
	s_waitcnt lgkmcnt(0)
	s_waitcnt lgkmcnt(0)
	v_mfma_f32_16x16x32_bf16 v[38:41], v[140:143], v[166:169], v[38:41]
	v_mfma_f32_16x16x32_bf16 v[18:21], v[152:155], v[166:169], v[18:21]
	v_mfma_f32_16x16x32_bf16 v[10:13], v[140:143], v[174:177], v[10:13]
	v_mfma_f32_16x16x32_bf16 v[2:5], v[152:155], v[174:177], v[2:5]
	v_mfma_f32_16x16x32_bf16 v[46:49], v[140:143], v[182:185], v[46:49]
	v_mfma_f32_16x16x32_bf16 v[30:33], v[152:155], v[182:185], v[30:33]
	v_mfma_f32_16x16x32_bf16 v[14:17], v[140:143], v[190:193], v[14:17]
	v_mfma_f32_16x16x32_bf16 v[6:9], v[152:155], v[190:193], v[6:9]
	v_mfma_f32_16x16x32_bf16 v[38:41], v[148:151], v[170:173], v[38:41]
	v_mfma_f32_16x16x32_bf16 v[18:21], v[156:159], v[170:173], v[18:21]
	v_mfma_f32_16x16x32_bf16 v[10:13], v[148:151], v[178:181], v[10:13]
	v_mfma_f32_16x16x32_bf16 v[2:5], v[156:159], v[178:181], v[2:5]
	v_mfma_f32_16x16x32_bf16 v[46:49], v[148:151], v[186:189], v[46:49]
	v_mfma_f32_16x16x32_bf16 v[30:33], v[156:159], v[186:189], v[30:33]
	v_mfma_f32_16x16x32_bf16 v[14:17], v[148:151], v[194:197], v[14:17]
	v_mfma_f32_16x16x32_bf16 v[6:9], v[156:159], v[194:197], v[6:9]
	s_barrier
	s_add_u32 s80, s0, 0x40000
	s_addc_u32 s81, s1, 0
	s_mov_b32 m0, s14
	s_nop 0
	global_load_lds_dwordx4 v0, s[80:81]
	s_mov_b32 m0, s15
	s_nop 0
	global_load_lds_dwordx4 v130, s[80:81]
	s_waitcnt vmcnt(6)
	s_barrier
; #define PG8_STAGE(bufoff, gbase, voff) do { _Pragma("unroll") for (int _i = 0; _i < 2; ++_i) \
;     __builtin_amdgcn_global_load_lds((const unsigned*)((const char*)(gbase) + (voff)[_i]), (PG8_LAS unsigned*)(lds + (bufoff) + ldsw + _i * 8192), 16, 0, 0); } while (0)
; #define PG8_LDA(dst, b, h) do { _Pragma("unroll") for (int m = 0; m < 4; ++m) _Pragma("unroll") for (int k = 0; k < 2; ++k) dst[m][k] = *(const PG8_LAS bf16x8*)(lds + PG8_SA(b, h) + aoff + m * 2048 + k * 1024); } while (0)
; #define PG8_LDB(dst, b, h) do { _Pragma("unroll") for (int n = 0; n < 2; ++n) _Pragma("unroll") for (int k = 0; k < 2; ++k) dst[n][k] = *(const PG8_LAS bf16x8*)(lds + PG8_SB(b, h) + boff + n * 2048 + k * 1024); } while (0)
; #define PG8_MMA(ai, bj, At, Bt) do { __builtin_amdgcn_s_setprio(1); _Pragma("unroll") for (int m = 0; m < 4; ++m) _Pragma("unroll") for (int n = 0; n < 2; ++n) _Pragma("unroll") for (int k = 0; k < 2; ++k) \
;     acc[ai][bj][m][n] = __builtin_amdgcn_mfma_f32_16x16x32_bf16(Bt[n][k], At[m][k], acc[ai][bj][m][n], 0, 0, 0); __builtin_amdgcn_s_setprio(0); } while (0)
; #define PG8_WAIT_V(n) asm volatile("s_waitcnt vmcnt(" #n ")" ::: "memory")
; #define PG8_WAIT_L(n) asm volatile("s_waitcnt lgkmcnt(" #n ")" ::: "memory")
; #define PG8_BAR __builtin_amdgcn_s_barrier()
; #define PG8_SCHED __builtin_amdgcn_sched_barrier(0)
; template <class Epi>
; DI void gemm_phase(const bf16_t* __restrict__ gA, const bf16_t* __restrict__ gBt, int M, int N, int K, const Epi& E, char* lds_generic) {
;     ...
;       PG8_WAIT_V(6); PG8_BAR; PG8_MMA(1, 1, At, B1); PG8_BAR;
;       PG8_LDB(B0, 1, 0); PG8_SCHED; PG8_LDA(At, 1, 0); PG8_STAGE(PG8_SA(0, 1), a2 + hstep, voffA);
;       PG8_WAIT_L(8); PG8_BAR; PG8_WAIT_L(0); PG8_MMA(0, 0, At, B0); PG8_BAR; PG8_SCHED;
;       PG8_LDB(B1, 1, 1); PG8_STAGE(PG8_SB(1, 0), b3, voffB);
;       PG8_BAR; PG8_WAIT_L(0); PG8_MMA(0, 1, At, B1); PG8_BAR;
;       PG8_LDA(At, 1, 1); PG8_STAGE(PG8_SA(1, 0), a3, voffA);
	v_mfma_f32_16x16x32_bf16 v[54:57], v[198:201], v[166:169], v[54:57]
	v_mfma_f32_16x16x32_bf16 v[66:69], v[206:209], v[166:169], v[66:69]
	v_mfma_f32_16x16x32_bf16 v[94:97], v[198:201], v[174:177], v[94:97]
	v_mfma_f32_16x16x32_bf16 v[106:109], v[206:209], v[174:177], v[106:109]
	v_mfma_f32_16x16x32_bf16 v[70:73], v[198:201], v[182:185], v[70:73]
	v_mfma_f32_16x16x32_bf16 v[78:81], v[206:209], v[182:185], v[78:81]
	v_mfma_f32_16x16x32_bf16 v[26:29], v[198:201], v[190:193], v[26:29]
	v_mfma_f32_16x16x32_bf16 v[34:37], v[206:209], v[190:193], v[34:37]
	v_mfma_f32_16x16x32_bf16 v[54:57], v[202:205], v[170:173], v[54:57]
	v_mfma_f32_16x16x32_bf16 v[66:69], v[210:213], v[170:173], v[66:69]
	v_mfma_f32_16x16x32_bf16 v[94:97], v[202:205], v[178:181], v[94:97]
	v_mfma_f32_16x16x32_bf16 v[106:109], v[210:213], v[178:181], v[106:109]
	v_mfma_f32_16x16x32_bf16 v[70:73], v[202:205], v[186:189], v[70:73]
	v_mfma_f32_16x16x32_bf16 v[78:81], v[210:213], v[186:189], v[78:81]
	v_mfma_f32_16x16x32_bf16 v[26:29], v[202:205], v[194:197], v[26:29]
	v_mfma_f32_16x16x32_bf16 v[34:37], v[210:213], v[194:197], v[34:37]
	v_or_b32_e32 v140, 0x18000, v146
	v_add_u32_e32 v148, 0x18400, v146
	v_add_u32_e32 v152, 0x18800, v146
	v_add_u32_e32 v156, 0x18c00, v146
	s_barrier
	ds_read_b128 v[140:143], v140
	ds_read_b128 v[148:151], v148
	ds_read_b128 v[152:155], v152
	ds_read_b128 v[156:159], v156
	s_add_u32 s30, s30, 0x40000
	s_addc_u32 s31, s31, 0
	s_mov_b32 m0, s16
	ds_read_b128 v[166:169], v145 offset:32768
	ds_read_b128 v[170:173], v145 offset:33792
	ds_read_b128 v[174:177], v145 offset:34816
	ds_read_b128 v[178:181], v145 offset:35840
	ds_read_b128 v[182:185], v145 offset:36864
	ds_read_b128 v[186:189], v145 offset:37888
	ds_read_b128 v[190:193], v145 offset:38912
	ds_read_b128 v[194:197], v145 offset:39936
	global_load_lds_dwordx4 v134, s[30:31]
	s_mov_b32 m0, s18
	s_nop 0
	global_load_lds_dwordx4 v132, s[30:31]
	s_barrier
	s_waitcnt lgkmcnt(0)
	s_waitcnt lgkmcnt(0)
	v_mfma_f32_16x16x32_bf16 v[118:121], v[140:143], v[166:169], v[118:121]
	v_mfma_f32_16x16x32_bf16 v[110:113], v[152:155], v[166:169], v[110:113]
	v_mfma_f32_16x16x32_bf16 v[90:93], v[140:143], v[174:177], v[90:93]
	v_mfma_f32_16x16x32_bf16 v[82:85], v[152:155], v[174:177], v[82:85]
	v_mfma_f32_16x16x32_bf16 v[62:65], v[140:143], v[182:185], v[62:65]
	v_mfma_f32_16x16x32_bf16 v[50:53], v[152:155], v[182:185], v[50:53]
	v_mfma_f32_16x16x32_bf16 v[42:45], v[140:143], v[190:193], v[42:45]
	v_mfma_f32_16x16x32_bf16 v[22:25], v[152:155], v[190:193], v[22:25]
	v_mfma_f32_16x16x32_bf16 v[118:121], v[148:151], v[170:173], v[118:121]
	v_mfma_f32_16x16x32_bf16 v[110:113], v[156:159], v[170:173], v[110:113]
	v_mfma_f32_16x16x32_bf16 v[90:93], v[148:151], v[178:181], v[90:93]
	v_mfma_f32_16x16x32_bf16 v[82:85], v[156:159], v[178:181], v[82:85]
	v_mfma_f32_16x16x32_bf16 v[62:65], v[148:151], v[186:189], v[62:65]
	v_mfma_f32_16x16x32_bf16 v[50:53], v[156:159], v[186:189], v[50:53]
	v_mfma_f32_16x16x32_bf16 v[42:45], v[148:151], v[194:197], v[42:45]
	v_mfma_f32_16x16x32_bf16 v[22:25], v[156:159], v[194:197], v[22:25]
	s_barrier
	v_or_b32_e32 v163, 0x1c000, v146
	s_mov_b32 m0, s8
	v_add_u32_e32 v165, 0x1c400, v146
	ds_read_b128 v[198:201], v163
	ds_read_b128 v[202:205], v165
	v_add_u32_e32 v163, 0x1c800, v146
	v_add_u32_e32 v165, 0x1cc00, v146
	ds_read_b128 v[206:209], v163
	ds_read_b128 v[210:213], v165
	s_add_u32 s80, s0, 0x80
	s_addc_u32 s81, s1, 0
	global_load_lds_dwordx4 v0, s[80:81]
	s_mov_b32 m0, s9
	s_nop 0
	s_add_u32 s80, s0, 0x80
	s_addc_u32 s81, s1, 0
	global_load_lds_dwordx4 v130, s[80:81]
	s_barrier
	s_waitcnt lgkmcnt(0)
	s_waitcnt lgkmcnt(0)
	v_mfma_f32_16x16x32_bf16 v[122:125], v[198:201], v[166:169], v[122:125]
	v_mfma_f32_16x16x32_bf16 v[126:129], v[206:209], v[166:169], v[126:129]
	v_mfma_f32_16x16x32_bf16 v[102:105], v[198:201], v[174:177], v[102:105]
	v_mfma_f32_16x16x32_bf16 v[114:117], v[206:209], v[174:177], v[114:117]
	v_mfma_f32_16x16x32_bf16 v[86:89], v[198:201], v[182:185], v[86:89]
	v_mfma_f32_16x16x32_bf16 v[98:101], v[206:209], v[182:185], v[98:101]
	v_mfma_f32_16x16x32_bf16 v[58:61], v[198:201], v[190:193], v[58:61]
	v_mfma_f32_16x16x32_bf16 v[74:77], v[206:209], v[190:193], v[74:77]
	v_mfma_f32_16x16x32_bf16 v[122:125], v[202:205], v[170:173], v[122:125]
	v_mfma_f32_16x16x32_bf16 v[126:129], v[210:213], v[170:173], v[126:129]
	v_mfma_f32_16x16x32_bf16 v[102:105], v[202:205], v[178:181], v[102:105]
	v_mfma_f32_16x16x32_bf16 v[114:117], v[210:213], v[178:181], v[114:117]
	v_mfma_f32_16x16x32_bf16 v[86:89], v[202:205], v[186:189], v[86:89]
	v_mfma_f32_16x16x32_bf16 v[98:101], v[210:213], v[186:189], v[98:101]
	v_mfma_f32_16x16x32_bf16 v[58:61], v[202:205], v[194:197], v[58:61]
	v_mfma_f32_16x16x32_bf16 v[74:77], v[210:213], v[194:197], v[74:77]
	s_mov_b32 m0, s19
	s_barrier
; DI bf16_t f2bf(float x) { unsigned u = __float_as_uint(x); u += 0x7fffu + ((u >> 16) & 1u); return (bf16_t)(u >> 16); }
; DI unsigned pack2(float lo, float hi) { f32x2_t v = {lo, hi}; return __builtin_bit_cast(unsigned, __builtin_convertvector(v, bf16x2_t)); }
; #define PG8_LAS __attribute__((address_space(3)))
; #define PG8_STAGE(bufoff, gbase, voff) do { _Pragma("unroll") for (int _i = 0; _i < 2; ++_i) \
;     __builtin_amdgcn_global_load_lds((const unsigned*)((const char*)(gbase) + (voff)[_i]), (PG8_LAS unsigned*)(lds + (bufoff) + ldsw + _i * 8192), 16, 0, 0); } while (0)
; #define PG8_LDA(dst, b, h) do { _Pragma("unroll") for (int m = 0; m < 4; ++m) _Pragma("unroll") for (int k = 0; k < 2; ++k) dst[m][k] = *(const PG8_LAS bf16x8*)(lds + PG8_SA(b, h) + aoff + m * 2048 + k * 1024); } while (0)
; #define PG8_WAIT_V(n) asm volatile("s_waitcnt vmcnt(" #n ")" ::: "memory")
; #define PG8_BAR __builtin_amdgcn_s_barrier()
;   DI void operator()(const f32x4 (&acc)[2][2][4][2], const Unit& u, int wr, int wc, int fr, int fq, const PG8_LAS float*) const {
;     const int row0 = u.pm * BM + wr * 64 + fr, col0 = u.pn * BM + wc * 32 + 8 * fq;
; #pragma unroll
;     for (int ai = 0; ai < 2; ++ai)
; #pragma unroll
;       for (int m = 0; m < 4; ++m) { const int row = row0 + ai * HALF + m * 16; bf16_t* rowp = dst + (size_t)row * DM + col0; float ss = 0.f;
; #pragma unroll
;         for (int bj = 0; bj < 2; ++bj) { const f32x4 v0 = acc[ai][bj][m][0] * coef, v1 = acc[ai][bj][m][1] * coef;
;           ss += v0[0] * v0[0] + v0[1] * v0[1] + v0[2] * v0[2] + v0[3] * v0[3] + v1[0] * v1[0] + v1[1] * v1[1] + v1[2] * v1[2] + v1[3] * v1[3];
;           u32x4 w; w.x = pack2(v0[0], v0[1]); w.y = pack2(v0[2], v0[3]); w.z = pack2(v1[0], v1[1]); w.w = pack2(v1[2], v1[3]);
;           *(u32x4*)(rowp + bj * HALF) = w; }
;         ss += __shfl_xor(ss, 16); ss += __shfl_xor(ss, 32);
;         if (fq == 0) ssq[(size_t)row * 16 + u.pn * 4 + wc] = f2bf(ss); }
; template <class Epi>
; DI void gemm_phase(const bf16_t* __restrict__ gA, const bf16_t* __restrict__ gBt, int M, int N, int K, const Epi& E, char* lds_generic) {
;     ...
;       PG8_LDA(At, 1, 1); PG8_STAGE(PG8_SA(1, 0), a3, voffA);
;       PG8_BAR; PG8_WAIT_L(0); PG8_MMA(1, 0, At, B0); PG8_BAR; PG8_SCHED;
;       PG8_STAGE(PG8_SB(1, 1), b3 + hstep, voffB);
;       PG8_WAIT_V(6); PG8_BAR; PG8_MMA(1, 1, At, B1); PG8_BAR;
	ds_read_b128 v[166:169], v145 offset:49152
	ds_read_b128 v[170:173], v145 offset:50176
	ds_read_b128 v[174:177], v145 offset:51200
	ds_read_b128 v[178:181], v145 offset:52224
	ds_read_b128 v[182:185], v145 offset:53248
	ds_read_b128 v[186:189], v145 offset:54272
	ds_read_b128 v[190:193], v145 offset:55296
	ds_read_b128 v[194:197], v145 offset:56320
	s_add_u32 s80, s30, 0xfffc0080
	s_addc_u32 s81, s31, -1
	global_load_lds_dwordx4 v134, s[80:81]
	s_mov_b32 m0, s33
	s_nop 0
	s_add_u32 s80, s30, 0xfffc0080
	s_addc_u32 s81, s31, -1
	global_load_lds_dwordx4 v132, s[80:81]
	s_barrier
	s_waitcnt lgkmcnt(0)
	s_waitcnt lgkmcnt(0)
	v_mfma_f32_16x16x32_bf16 v[38:41], v[140:143], v[166:169], v[38:41]
	v_mfma_f32_16x16x32_bf16 v[18:21], v[152:155], v[166:169], v[18:21]
	v_mfma_f32_16x16x32_bf16 v[10:13], v[140:143], v[174:177], v[10:13]
	v_mfma_f32_16x16x32_bf16 v[2:5], v[152:155], v[174:177], v[2:5]
	v_mfma_f32_16x16x32_bf16 v[46:49], v[140:143], v[182:185], v[46:49]
	v_mfma_f32_16x16x32_bf16 v[30:33], v[152:155], v[182:185], v[30:33]
	v_mfma_f32_16x16x32_bf16 v[14:17], v[140:143], v[190:193], v[14:17]
	v_mfma_f32_16x16x32_bf16 v[6:9], v[152:155], v[190:193], v[6:9]
	v_mfma_f32_16x16x32_bf16 v[38:41], v[148:151], v[170:173], v[38:41]
	v_mfma_f32_16x16x32_bf16 v[18:21], v[156:159], v[170:173], v[18:21]
	v_mfma_f32_16x16x32_bf16 v[10:13], v[148:151], v[178:181], v[10:13]
	v_mfma_f32_16x16x32_bf16 v[2:5], v[156:159], v[178:181], v[2:5]
	v_mfma_f32_16x16x32_bf16 v[46:49], v[148:151], v[186:189], v[46:49]
	v_mfma_f32_16x16x32_bf16 v[30:33], v[156:159], v[186:189], v[30:33]
	v_mfma_f32_16x16x32_bf16 v[14:17], v[148:151], v[194:197], v[14:17]
	v_mfma_f32_16x16x32_bf16 v[6:9], v[156:159], v[194:197], v[6:9]
	s_barrier
	s_add_u32 s0, s0, 0x40080
	s_addc_u32 s1, s1, 0
	s_mov_b32 m0, s35
	s_nop 0
	global_load_lds_dwordx4 v0, s[0:1]
	s_mov_b32 m0, s42
	s_nop 0
	global_load_lds_dwordx4 v130, s[0:1]
	s_waitcnt vmcnt(6)
	s_barrier
	v_mfma_f32_16x16x32_bf16 v[54:57], v[198:201], v[166:169], v[54:57]
	v_mfma_f32_16x16x32_bf16 v[66:69], v[206:209], v[166:169], v[66:69]
	v_mfma_f32_16x16x32_bf16 v[94:97], v[198:201], v[174:177], v[94:97]
	v_mfma_f32_16x16x32_bf16 v[106:109], v[206:209], v[174:177], v[106:109]
	v_mfma_f32_16x16x32_bf16 v[70:73], v[198:201], v[182:185], v[70:73]
	v_mfma_f32_16x16x32_bf16 v[78:81], v[206:209], v[182:185], v[78:81]
	v_mfma_f32_16x16x32_bf16 v[26:29], v[198:201], v[190:193], v[26:29]
	v_mfma_f32_16x16x32_bf16 v[34:37], v[206:209], v[190:193], v[34:37]
	v_mfma_f32_16x16x32_bf16 v[54:57], v[202:205], v[170:173], v[54:57]
	v_mfma_f32_16x16x32_bf16 v[66:69], v[210:213], v[170:173], v[66:69]
	v_mfma_f32_16x16x32_bf16 v[94:97], v[202:205], v[178:181], v[94:97]
	v_mfma_f32_16x16x32_bf16 v[106:109], v[210:213], v[178:181], v[106:109]
	v_mfma_f32_16x16x32_bf16 v[70:73], v[202:205], v[186:189], v[70:73]
	v_mfma_f32_16x16x32_bf16 v[78:81], v[210:213], v[186:189], v[78:81]
	v_mfma_f32_16x16x32_bf16 v[26:29], v[202:205], v[194:197], v[26:29]
	v_mfma_f32_16x16x32_bf16 v[34:37], v[210:213], v[194:197], v[34:37]
	s_add_i32 s60, s60, 2
	s_add_u32 s28, s28, 0x100
	s_addc_u32 s29, s29, 0
	s_add_u32 s58, s58, 0x100
	s_addc_u32 s59, s59, 0
	s_cmp_gt_u32 s60, 13
	s_barrier
	s_cbranch_scc0 .LBB0_511
	v_mul_f32_e32 v152, v119, v119
	v_fmac_f32_e32 v152, v118, v118
	v_fmac_f32_e32 v152, v120, v120
	v_cvt_pk_bf16_f32 v118, v118, v119
	v_cvt_pk_bf16_f32 v119, v120, v121
	v_mul_f32_e32 v120, v123, v123
	v_fmac_f32_e32 v120, v122, v122
	v_fmac_f32_e32 v120, v124, v124
	v_fmac_f32_e32 v152, v121, v121
	v_fmac_f32_e32 v120, v125, v125
	v_fmac_f32_e32 v152, v110, v110
	v_fmac_f32_e32 v120, v126, v126
	v_xor_b32_e32 v143, 16, v223
	v_fmac_f32_e32 v152, v111, v111
	v_fmac_f32_e32 v120, v127, v127
	v_cmp_lt_i32_e64 s[0:1], v143, v225
	v_fmac_f32_e32 v152, v112, v112
	v_fmac_f32_e32 v120, v128, v128
	v_cndmask_b32_e64 v143, v223, v143, s[0:1]
	v_fmac_f32_e32 v152, v113, v113
	v_fmac_f32_e32 v120, v129, v129
	v_lshlrev_b32_e32 v149, 2, v143
	v_add_f32_e32 v152, v152, v120
	ds_bpermute_b32 v153, v149, v152
	v_xor_b32_e32 v143, 32, v223
	v_cmp_lt_i32_e64 s[0:1], v143, v225
	v_lshl_add_u32 v142, s21, 8, v144
	v_cvt_pk_bf16_f32 v120, v110, v111
	v_cndmask_b32_e64 v143, v223, v143, s[0:1]
	v_lshlrev_b32_e32 v148, 2, v143
	s_waitcnt lgkmcnt(0)
	v_add_f32_e32 v110, v152, v153
	v_ashrrev_i32_e32 v143, 31, v142
	ds_bpermute_b32 v111, v148, v110
	v_lshl_or_b32 v140, s20, 8, v147
	v_lshlrev_b64 v[150:151], 11, v[142:143]
	v_ashrrev_i32_e32 v141, 31, v140
	v_lshl_add_u64 v[150:151], s[92:93], 0, v[150:151]
	s_lshl_b32 s0, s20, 2
	v_lshl_add_u64 v[150:151], v[140:141], 1, v[150:151]
	v_cvt_pk_bf16_f32 v121, v112, v113
	s_ashr_i32 s1, s0, 31
	global_store_dwordx4 v[150:151], v[118:121], off
	s_nop 1
	v_cvt_pk_bf16_f32 v118, v122, v123
	v_cvt_pk_bf16_f32 v119, v124, v125
	v_cvt_pk_bf16_f32 v120, v126, v127
	v_cvt_pk_bf16_f32 v121, v128, v129
	global_store_dwordx4 v[150:151], v[118:121], off offset:256
	s_and_saveexec_b64 s[28:29], s[36:37]
	s_cbranch_execz .LBB0_514
	s_waitcnt lgkmcnt(0)
	v_add_f32_e32 v110, v110, v111
	v_bfe_u32 v111, v110, 16, 1
	v_add3_u32 v112, v110, v111, s63
	v_lshlrev_b64 v[110:111], 5, v[142:143]
	v_lshl_add_u64 v[110:111], s[70:71], 0, v[110:111]
	v_lshl_add_u64 v[110:111], s[0:1], 1, v[110:111]
	s_lshl_b32 s76, s5, 1
	v_lshl_add_u64 v[110:111], v[110:111], 0, s[76:77]
	global_store_short_d16_hi v[110:111], v112, off

; #define PG8_STAGE(bufoff, gbase, voff) do { _Pragma("unroll") for (int _i = 0; _i < 2; ++_i) \
;     __builtin_amdgcn_global_load_lds((const unsigned*)((const char*)(gbase) + (voff)[_i]), (PG8_LAS unsigned*)(lds + (bufoff) + ldsw + _i * 8192), 16, 0, 0); } while (0)
; #define PG8_LDA(dst, b, h) do { _Pragma("unroll") for (int m = 0; m < 4; ++m) _Pragma("unroll") for (int k = 0; k < 2; ++k) dst[m][k] = *(const PG8_LAS bf16x8*)(lds + PG8_SA(b, h) + aoff + m * 2048 + k * 1024); } while (0)
; #define PG8_LDB(dst, b, h) do { _Pragma("unroll") for (int n = 0; n < 2; ++n) _Pragma("unroll") for (int k = 0; k < 2; ++k) dst[n][k] = *(const PG8_LAS bf16x8*)(lds + PG8_SB(b, h) + boff + n * 2048 + k * 1024); } while (0)
; #define PG8_MMA(ai, bj, At, Bt) do { __builtin_amdgcn_s_setprio(1); _Pragma("unroll") for (int m = 0; m < 4; ++m) _Pragma("unroll") for (int n = 0; n < 2; ++n) _Pragma("unroll") for (int k = 0; k < 2; ++k) \
;     acc[ai][bj][m][n] = __builtin_amdgcn_mfma_f32_16x16x32_bf16(Bt[n][k], At[m][k], acc[ai][bj][m][n], 0, 0, 0); __builtin_amdgcn_s_setprio(0); } while (0)
; template <class Epi>
; DI void gemm_phase(const bf16_t* __restrict__ gA, const bf16_t* __restrict__ gBt, int M, int N, int K, const Epi& E, char* lds_generic) {
;     ...
;     const bool has_next = S.next(ui + 1, nxt);
;     const char* nA = has_next ? (const char*)gA + (size_t)nxt.pm * tstep : cA; const char* nB = has_next ? (const char*)gBt + (size_t)nxt.pn * tstep : cB;
;     for (int t = 0; t < nt; t += 2) {
;       const bool last = (t == nt - 2);
;       const char* a1 = cA + (size_t)(t + 1) * kstep;
;       const char* a2 = last ? nA : cA + (size_t)(t + 2) * kstep; const char* b2 = last ? nB : cB + (size_t)(t + 2) * kstep;
;       const char* a3 = a2 + kstep; const char* b3 = b2 + kstep;
;       PG8_LDB(B0, 0, 0); PG8_SCHED; PG8_LDA(At, 0, 0); PG8_STAGE(PG8_SA(1, 1), a1 + hstep, voffA);
;       PG8_WAIT_L(8); PG8_BAR; PG8_WAIT_L(0); PG8_MMA(0, 0, At, B0); PG8_BAR; PG8_SCHED;
;       PG8_LDB(B1, 0, 1); PG8_STAGE(PG8_SB(0, 0), b2, voffB);
;       PG8_BAR; PG8_WAIT_L(0); PG8_MMA(0, 1, At, B1); PG8_BAR;
;       PG8_LDA(At, 0, 1); PG8_STAGE(PG8_SA(0, 0), a2, voffA);
;       PG8_BAR; PG8_WAIT_L(0); PG8_MMA(1, 0, At, B0); PG8_BAR; PG8_SCHED;
;       PG8_STAGE(PG8_SB(0, 1), b2 + hstep, voffB);
;       PG8_WAIT_V(6); PG8_BAR; PG8_MMA(1, 1, At, B1); PG8_BAR;
.LBB0_604:
	s_ashr_i32 s87, s86, 31
	s_lshl_b64 s[20:21], s[86:87], 19
	s_add_u32 s88, s82, s20
	s_addc_u32 s89, s83, s21
	s_and_b64 s[20:21], s[38:39], exec
	s_cselect_b32 s20, s89, s29
	s_cselect_b32 s21, s88, s28
	s_ashr_i32 s27, s26, 31
	s_lshl_b64 s[22:23], s[26:27], 19
	s_add_u32 s90, s16, s22
	s_addc_u32 s91, s4, s23
	s_and_b64 s[22:23], s[38:39], exec
	s_cselect_b32 s27, s91, s31
	s_cselect_b32 s42, s90, s30
	s_add_u32 vcc_lo, s28, 0x40080
	s_addc_u32 vcc_hi, s29, 0
	s_add_u32 s87, s30, 0x100
	s_addc_u32 s22, s31, 0
	s_mov_b32 s23, -2
	v_or_b32_e32 v50, 0x10000, v155
	v_add_u32_e32 v146, 0x10400, v155
	v_add_u32_e32 v158, 0x10800, v155
	ds_read_b128 v[50:53], v50
	ds_read_b128 v[146:149], v146
	v_add_u32_e32 v163, 0x10c00, v155
	ds_read_b128 v[158:161], v158
	ds_read_b128 v[166:169], v163
	s_add_u32 s24, vcc_lo, 0xfffc0080
	s_addc_u32 s25, vcc_hi, -1
	s_cmp_eq_u32 s23, 12
	s_cselect_b32 s31, s20, s25
	s_cselect_b32 s30, s21, s24
	s_cselect_b32 s29, s27, s22
	s_cselect_b32 s28, s42, s87
	s_add_i32 m0, s72, 0xc000
	ds_read_b128 v[170:173], v154
	ds_read_b128 v[174:177], v154 offset:1024
	ds_read_b128 v[178:181], v154 offset:2048
	ds_read_b128 v[182:185], v154 offset:3072
	ds_read_b128 v[186:189], v154 offset:4096
	ds_read_b128 v[190:193], v154 offset:5120
	ds_read_b128 v[194:197], v154 offset:6144
	ds_read_b128 v[198:201], v154 offset:7168
	global_load_lds_dwordx4 v142, vcc
	s_add_i32 m0, s72, 0xe000
	s_nop 0
	global_load_lds_dwordx4 v144, vcc
	s_barrier
	s_waitcnt lgkmcnt(0)
	s_waitcnt lgkmcnt(0)
	v_mfma_f32_16x16x32_bf16 v[130:133], v[50:53], v[170:173], 0
	v_mfma_f32_16x16x32_bf16 v[122:125], v[158:161], v[170:173], 0
	v_mfma_f32_16x16x32_bf16 v[114:117], v[50:53], v[178:181], 0
	v_mfma_f32_16x16x32_bf16 v[106:109], v[158:161], v[178:181], 0
	v_mfma_f32_16x16x32_bf16 v[98:101], v[50:53], v[186:189], 0
	v_mfma_f32_16x16x32_bf16 v[90:93], v[158:161], v[186:189], 0
	v_mfma_f32_16x16x32_bf16 v[82:85], v[50:53], v[194:197], 0
	v_mfma_f32_16x16x32_bf16 v[74:77], v[158:161], v[194:197], 0
	v_mfma_f32_16x16x32_bf16 v[130:133], v[146:149], v[174:177], v[130:133]
	v_mfma_f32_16x16x32_bf16 v[122:125], v[166:169], v[174:177], v[122:125]
	v_mfma_f32_16x16x32_bf16 v[114:117], v[146:149], v[182:185], v[114:117]
	v_mfma_f32_16x16x32_bf16 v[106:109], v[166:169], v[182:185], v[106:109]
	v_mfma_f32_16x16x32_bf16 v[98:101], v[146:149], v[190:193], v[98:101]
	v_mfma_f32_16x16x32_bf16 v[90:93], v[166:169], v[190:193], v[90:93]
	v_mfma_f32_16x16x32_bf16 v[82:85], v[146:149], v[198:201], v[82:85]
	v_mfma_f32_16x16x32_bf16 v[74:77], v[166:169], v[198:201], v[74:77]
	s_barrier
	v_or_b32_e32 v163, 0x14000, v155
	s_mov_b32 m0, s14
	v_add_u32_e32 v165, 0x14400, v155
	ds_read_b128 v[202:205], v163
	ds_read_b128 v[206:209], v165
	v_add_u32_e32 v163, 0x14800, v155
	v_add_u32_e32 v165, 0x14c00, v155
	ds_read_b128 v[210:213], v163
	ds_read_b128 v[214:217], v165
	global_load_lds_dwordx4 v0, s[28:29]
	s_mov_b32 m0, s15
	s_nop 0
	global_load_lds_dwordx4 v138, s[28:29]
	s_barrier
	s_waitcnt lgkmcnt(0)
	s_waitcnt lgkmcnt(0)
	v_mfma_f32_16x16x32_bf16 v[126:129], v[202:205], v[170:173], 0
	v_mfma_f32_16x16x32_bf16 v[118:121], v[210:213], v[170:173], 0
	v_mfma_f32_16x16x32_bf16 v[110:113], v[202:205], v[178:181], 0
	v_mfma_f32_16x16x32_bf16 v[102:105], v[210:213], v[178:181], 0
	v_mfma_f32_16x16x32_bf16 v[94:97], v[202:205], v[186:189], 0
	v_mfma_f32_16x16x32_bf16 v[86:89], v[210:213], v[186:189], 0
	v_mfma_f32_16x16x32_bf16 v[78:81], v[202:205], v[194:197], 0
	v_mfma_f32_16x16x32_bf16 v[70:73], v[210:213], v[194:197], 0
	v_mfma_f32_16x16x32_bf16 v[126:129], v[206:209], v[174:177], v[126:129]
	v_mfma_f32_16x16x32_bf16 v[118:121], v[214:217], v[174:177], v[118:121]
	v_mfma_f32_16x16x32_bf16 v[110:113], v[206:209], v[182:185], v[110:113]
	v_mfma_f32_16x16x32_bf16 v[102:105], v[214:217], v[182:185], v[102:105]
	v_mfma_f32_16x16x32_bf16 v[94:97], v[206:209], v[190:193], v[94:97]
	v_mfma_f32_16x16x32_bf16 v[86:89], v[214:217], v[190:193], v[86:89]
	v_mfma_f32_16x16x32_bf16 v[78:81], v[206:209], v[198:201], v[78:81]
	v_mfma_f32_16x16x32_bf16 v[70:73], v[214:217], v[198:201], v[70:73]
	s_mov_b32 m0, s72
	s_barrier
	ds_read_b128 v[170:173], v154 offset:16384
	ds_read_b128 v[174:177], v154 offset:17408
	ds_read_b128 v[178:181], v154 offset:18432
	ds_read_b128 v[182:185], v154 offset:19456
	ds_read_b128 v[186:189], v154 offset:20480
	ds_read_b128 v[190:193], v154 offset:21504
	ds_read_b128 v[194:197], v154 offset:22528
	ds_read_b128 v[198:201], v154 offset:23552
	global_load_lds_dwordx4 v134, s[30:31]
	s_mov_b32 m0, s58
	s_nop 0
	global_load_lds_dwordx4 v136, s[30:31]
	s_barrier
	s_waitcnt lgkmcnt(0)
	s_waitcnt lgkmcnt(0)
	v_mfma_f32_16x16x32_bf16 v[66:69], v[50:53], v[170:173], 0
	v_mfma_f32_16x16x32_bf16 v[58:61], v[158:161], v[170:173], 0
	v_mfma_f32_16x16x32_bf16 v[46:49], v[50:53], v[178:181], 0
	v_mfma_f32_16x16x32_bf16 v[38:41], v[158:161], v[178:181], 0
	v_mfma_f32_16x16x32_bf16 v[30:33], v[50:53], v[186:189], 0
	v_mfma_f32_16x16x32_bf16 v[22:25], v[158:161], v[186:189], 0
	v_mfma_f32_16x16x32_bf16 v[14:17], v[50:53], v[194:197], 0
	v_mfma_f32_16x16x32_bf16 v[6:9], v[158:161], v[194:197], 0
	v_mfma_f32_16x16x32_bf16 v[66:69], v[146:149], v[174:177], v[66:69]
	v_mfma_f32_16x16x32_bf16 v[58:61], v[166:169], v[174:177], v[58:61]
	v_mfma_f32_16x16x32_bf16 v[46:49], v[146:149], v[182:185], v[46:49]
	v_mfma_f32_16x16x32_bf16 v[38:41], v[166:169], v[182:185], v[38:41]
	v_mfma_f32_16x16x32_bf16 v[30:33], v[146:149], v[190:193], v[30:33]
	v_mfma_f32_16x16x32_bf16 v[22:25], v[166:169], v[190:193], v[22:25]
	v_mfma_f32_16x16x32_bf16 v[14:17], v[146:149], v[198:201], v[14:17]
	v_mfma_f32_16x16x32_bf16 v[6:9], v[166:169], v[198:201], v[6:9]
	s_barrier
; #define PG8_STAGE(bufoff, gbase, voff) do { _Pragma("unroll") for (int _i = 0; _i < 2; ++_i) \
;     __builtin_amdgcn_global_load_lds((const unsigned*)((const char*)(gbase) + (voff)[_i]), (PG8_LAS unsigned*)(lds + (bufoff) + ldsw + _i * 8192), 16, 0, 0); } while (0)
; #define PG8_LDA(dst, b, h) do { _Pragma("unroll") for (int m = 0; m < 4; ++m) _Pragma("unroll") for (int k = 0; k < 2; ++k) dst[m][k] = *(const PG8_LAS bf16x8*)(lds + PG8_SA(b, h) + aoff + m * 2048 + k * 1024); } while (0)
; #define PG8_LDB(dst, b, h) do { _Pragma("unroll") for (int n = 0; n < 2; ++n) _Pragma("unroll") for (int k = 0; k < 2; ++k) dst[n][k] = *(const PG8_LAS bf16x8*)(lds + PG8_SB(b, h) + boff + n * 2048 + k * 1024); } while (0)
; #define PG8_MMA(ai, bj, At, Bt) do { __builtin_amdgcn_s_setprio(1); _Pragma("unroll") for (int m = 0; m < 4; ++m) _Pragma("unroll") for (int n = 0; n < 2; ++n) _Pragma("unroll") for (int k = 0; k < 2; ++k) \
;     acc[ai][bj][m][n] = __builtin_amdgcn_mfma_f32_16x16x32_bf16(Bt[n][k], At[m][k], acc[ai][bj][m][n], 0, 0, 0); __builtin_amdgcn_s_setprio(0); } while (0)
; #define PG8_WAIT_V(n) asm volatile("s_waitcnt vmcnt(" #n ")" ::: "memory")
; #define PG8_WAIT_L(n) asm volatile("s_waitcnt lgkmcnt(" #n ")" ::: "memory")
; #define PG8_BAR __builtin_amdgcn_s_barrier()
; #define PG8_SCHED __builtin_amdgcn_sched_barrier(0)
; template <class Epi>
; DI void gemm_phase(const bf16_t* __restrict__ gA, const bf16_t* __restrict__ gBt, int M, int N, int K, const Epi& E, char* lds_generic) {
;     ...
;       PG8_LDB(B0, 0, 0); PG8_SCHED; PG8_LDA(At, 0, 0); PG8_STAGE(PG8_SA(1, 1), a1 + hstep, voffA);
;       PG8_WAIT_L(8); PG8_BAR; PG8_WAIT_L(0); PG8_MMA(0, 0, At, B0); PG8_BAR; PG8_SCHED;
;       PG8_LDB(B1, 0, 1); PG8_STAGE(PG8_SB(0, 0), b2, voffB);
;       PG8_BAR; PG8_WAIT_L(0); PG8_MMA(0, 1, At, B1); PG8_BAR;
;       PG8_LDA(At, 0, 1); PG8_STAGE(PG8_SA(0, 0), a2, voffA);
;       PG8_BAR; PG8_WAIT_L(0); PG8_MMA(1, 0, At, B0); PG8_BAR; PG8_SCHED;
;       PG8_STAGE(PG8_SB(0, 1), b2 + hstep, voffB);
;       PG8_WAIT_V(6); PG8_BAR; PG8_MMA(1, 1, At, B1); PG8_BAR;
	s_add_u32 s24, s28, 0x40000
	s_addc_u32 s25, s29, 0
	s_mov_b32 m0, s59
	s_nop 0
	global_load_lds_dwordx4 v0, s[24:25]
	s_mov_b32 m0, s62
	s_nop 0
	global_load_lds_dwordx4 v138, s[24:25]
	s_waitcnt vmcnt(6)
	s_barrier
	v_mfma_f32_16x16x32_bf16 v[54:57], v[210:213], v[170:173], 0
	v_mfma_f32_16x16x32_bf16 v[42:45], v[202:205], v[178:181], 0
	v_mfma_f32_16x16x32_bf16 v[34:37], v[210:213], v[178:181], 0
	v_mfma_f32_16x16x32_bf16 v[26:29], v[202:205], v[186:189], 0
	v_mfma_f32_16x16x32_bf16 v[18:21], v[210:213], v[186:189], 0
	v_mfma_f32_16x16x32_bf16 v[10:13], v[202:205], v[194:197], 0
	v_mfma_f32_16x16x32_bf16 v[2:5], v[210:213], v[194:197], 0
	v_mfma_f32_16x16x32_bf16 v[50:53], v[202:205], v[170:173], 0
	v_mfma_f32_16x16x32_bf16 v[54:57], v[214:217], v[174:177], v[54:57]
	v_mfma_f32_16x16x32_bf16 v[42:45], v[206:209], v[182:185], v[42:45]
	v_mfma_f32_16x16x32_bf16 v[34:37], v[214:217], v[182:185], v[34:37]
	v_mfma_f32_16x16x32_bf16 v[26:29], v[206:209], v[190:193], v[26:29]
	v_mfma_f32_16x16x32_bf16 v[18:21], v[214:217], v[190:193], v[18:21]
	v_mfma_f32_16x16x32_bf16 v[10:13], v[206:209], v[198:201], v[10:13]
	v_mfma_f32_16x16x32_bf16 v[2:5], v[214:217], v[198:201], v[2:5]
	v_mfma_f32_16x16x32_bf16 v[50:53], v[206:209], v[174:177], v[50:53]
	v_or_b32_e32 v62, 0x18000, v155
	v_add_u32_e32 v146, 0x18400, v155
	v_add_u32_e32 v158, 0x18800, v155
	s_barrier
	s_branch .Lup605_p5
.LBB0_605:
	v_or_b32_e32 v50, 0x10000, v155
	v_add_u32_e32 v146, 0x10400, v155
	v_add_u32_e32 v158, 0x10800, v155
	ds_read_b128 v[50:53], v50
	ds_read_b128 v[146:149], v146
	v_add_u32_e32 v163, 0x10c00, v155
	ds_read_b128 v[158:161], v158
	ds_read_b128 v[166:169], v163
	s_add_u32 s24, vcc_lo, 0xfffc0080
	s_addc_u32 s25, vcc_hi, -1
	s_cmp_eq_u32 s23, 12
	s_cselect_b32 s31, s20, s25
	s_cselect_b32 s30, s21, s24
	s_cselect_b32 s29, s27, s22
	s_cselect_b32 s28, s42, s87
	s_add_i32 m0, s72, 0xc000
	ds_read_b128 v[170:173], v154
	ds_read_b128 v[174:177], v154 offset:1024
	ds_read_b128 v[178:181], v154 offset:2048
	ds_read_b128 v[182:185], v154 offset:3072
	ds_read_b128 v[186:189], v154 offset:4096
	ds_read_b128 v[190:193], v154 offset:5120
	ds_read_b128 v[194:197], v154 offset:6144
	ds_read_b128 v[198:201], v154 offset:7168
	global_load_lds_dwordx4 v142, vcc
	s_add_i32 m0, s72, 0xe000
	s_nop 0
	global_load_lds_dwordx4 v144, vcc
	s_barrier
	s_waitcnt lgkmcnt(0)
	s_waitcnt lgkmcnt(0)
	v_mfma_f32_16x16x32_bf16 v[130:133], v[50:53], v[170:173], v[130:133]
	v_mfma_f32_16x16x32_bf16 v[122:125], v[158:161], v[170:173], v[122:125]
	v_mfma_f32_16x16x32_bf16 v[114:117], v[50:53], v[178:181], v[114:117]
	v_mfma_f32_16x16x32_bf16 v[106:109], v[158:161], v[178:181], v[106:109]
	v_mfma_f32_16x16x32_bf16 v[98:101], v[50:53], v[186:189], v[98:101]
	v_mfma_f32_16x16x32_bf16 v[90:93], v[158:161], v[186:189], v[90:93]
	v_mfma_f32_16x16x32_bf16 v[82:85], v[50:53], v[194:197], v[82:85]
	v_mfma_f32_16x16x32_bf16 v[74:77], v[158:161], v[194:197], v[74:77]
	v_mfma_f32_16x16x32_bf16 v[130:133], v[146:149], v[174:177], v[130:133]
	v_mfma_f32_16x16x32_bf16 v[122:125], v[166:169], v[174:177], v[122:125]
	v_mfma_f32_16x16x32_bf16 v[114:117], v[146:149], v[182:185], v[114:117]
	v_mfma_f32_16x16x32_bf16 v[106:109], v[166:169], v[182:185], v[106:109]
	v_mfma_f32_16x16x32_bf16 v[98:101], v[146:149], v[190:193], v[98:101]
	v_mfma_f32_16x16x32_bf16 v[90:93], v[166:169], v[190:193], v[90:93]
	v_mfma_f32_16x16x32_bf16 v[82:85], v[146:149], v[198:201], v[82:85]
	v_mfma_f32_16x16x32_bf16 v[74:77], v[166:169], v[198:201], v[74:77]
	s_barrier
	v_or_b32_e32 v163, 0x14000, v155
	s_mov_b32 m0, s14
	v_add_u32_e32 v165, 0x14400, v155
	ds_read_b128 v[202:205], v163
	ds_read_b128 v[206:209], v165
	v_add_u32_e32 v163, 0x14800, v155
	v_add_u32_e32 v165, 0x14c00, v155
	ds_read_b128 v[210:213], v163
	ds_read_b128 v[214:217], v165
	global_load_lds_dwordx4 v0, s[28:29]
	s_mov_b32 m0, s15
	s_nop 0
	global_load_lds_dwordx4 v138, s[28:29]
	s_barrier
	s_waitcnt lgkmcnt(0)
	s_waitcnt lgkmcnt(0)
	v_mfma_f32_16x16x32_bf16 v[126:129], v[202:205], v[170:173], v[126:129]
	v_mfma_f32_16x16x32_bf16 v[118:121], v[210:213], v[170:173], v[118:121]
	v_mfma_f32_16x16x32_bf16 v[110:113], v[202:205], v[178:181], v[110:113]
	v_mfma_f32_16x16x32_bf16 v[102:105], v[210:213], v[178:181], v[102:105]
	v_mfma_f32_16x16x32_bf16 v[94:97], v[202:205], v[186:189], v[94:97]
	v_mfma_f32_16x16x32_bf16 v[86:89], v[210:213], v[186:189], v[86:89]
	v_mfma_f32_16x16x32_bf16 v[78:81], v[202:205], v[194:197], v[78:81]
	v_mfma_f32_16x16x32_bf16 v[70:73], v[210:213], v[194:197], v[70:73]
	v_mfma_f32_16x16x32_bf16 v[126:129], v[206:209], v[174:177], v[126:129]
	v_mfma_f32_16x16x32_bf16 v[118:121], v[214:217], v[174:177], v[118:121]
	v_mfma_f32_16x16x32_bf16 v[110:113], v[206:209], v[182:185], v[110:113]
	v_mfma_f32_16x16x32_bf16 v[102:105], v[214:217], v[182:185], v[102:105]
	v_mfma_f32_16x16x32_bf16 v[94:97], v[206:209], v[190:193], v[94:97]
	v_mfma_f32_16x16x32_bf16 v[86:89], v[214:217], v[190:193], v[86:89]
	v_mfma_f32_16x16x32_bf16 v[78:81], v[206:209], v[198:201], v[78:81]
	v_mfma_f32_16x16x32_bf16 v[70:73], v[214:217], v[198:201], v[70:73]
	s_mov_b32 m0, s72
	s_barrier
	ds_read_b128 v[170:173], v154 offset:16384
	ds_read_b128 v[174:177], v154 offset:17408
	ds_read_b128 v[178:181], v154 offset:18432
	ds_read_b128 v[182:185], v154 offset:19456
	ds_read_b128 v[186:189], v154 offset:20480
	ds_read_b128 v[190:193], v154 offset:21504
	ds_read_b128 v[194:197], v154 offset:22528
	ds_read_b128 v[198:201], v154 offset:23552
	global_load_lds_dwordx4 v134, s[30:31]
	s_mov_b32 m0, s58
	s_nop 0
	global_load_lds_dwordx4 v136, s[30:31]
	s_barrier
; #define PG8_STAGE(bufoff, gbase, voff) do { _Pragma("unroll") for (int _i = 0; _i < 2; ++_i) \
;     __builtin_amdgcn_global_load_lds((const unsigned*)((const char*)(gbase) + (voff)[_i]), (PG8_LAS unsigned*)(lds + (bufoff) + ldsw + _i * 8192), 16, 0, 0); } while (0)
; #define PG8_LDA(dst, b, h) do { _Pragma("unroll") for (int m = 0; m < 4; ++m) _Pragma("unroll") for (int k = 0; k < 2; ++k) dst[m][k] = *(const PG8_LAS bf16x8*)(lds + PG8_SA(b, h) + aoff + m * 2048 + k * 1024); } while (0)
; #define PG8_LDB(dst, b, h) do { _Pragma("unroll") for (int n = 0; n < 2; ++n) _Pragma("unroll") for (int k = 0; k < 2; ++k) dst[n][k] = *(const PG8_LAS bf16x8*)(lds + PG8_SB(b, h) + boff + n * 2048 + k * 1024); } while (0)
; #define PG8_MMA(ai, bj, At, Bt) do { __builtin_amdgcn_s_setprio(1); _Pragma("unroll") for (int m = 0; m < 4; ++m) _Pragma("unroll") for (int n = 0; n < 2; ++n) _Pragma("unroll") for (int k = 0; k < 2; ++k) \
;     acc[ai][bj][m][n] = __builtin_amdgcn_mfma_f32_16x16x32_bf16(Bt[n][k], At[m][k], acc[ai][bj][m][n], 0, 0, 0); __builtin_amdgcn_s_setprio(0); } while (0)
; #define PG8_WAIT_V(n) asm volatile("s_waitcnt vmcnt(" #n ")" ::: "memory")
; #define PG8_WAIT_L(n) asm volatile("s_waitcnt lgkmcnt(" #n ")" ::: "memory")
; #define PG8_BAR __builtin_amdgcn_s_barrier()
; #define PG8_SCHED __builtin_amdgcn_sched_barrier(0)
; template <class Epi>
; DI void gemm_phase(const bf16_t* __restrict__ gA, const bf16_t* __restrict__ gBt, int M, int N, int K, const Epi& E, char* lds_generic) {
;     ...
;       PG8_WAIT_V(6); PG8_BAR; PG8_MMA(1, 1, At, B1); PG8_BAR;
;       PG8_LDB(B0, 1, 0); PG8_SCHED; PG8_LDA(At, 1, 0); PG8_STAGE(PG8_SA(0, 1), a2 + hstep, voffA);
;       PG8_WAIT_L(8); PG8_BAR; PG8_WAIT_L(0); PG8_MMA(0, 0, At, B0); PG8_BAR; PG8_SCHED;
;       PG8_LDB(B1, 1, 1); PG8_STAGE(PG8_SB(1, 0), b3, voffB);
;       PG8_BAR; PG8_WAIT_L(0); PG8_MMA(0, 1, At, B1); PG8_BAR;
	s_waitcnt lgkmcnt(0)
	s_waitcnt lgkmcnt(0)
	v_mfma_f32_16x16x32_bf16 v[66:69], v[50:53], v[170:173], v[66:69]
	v_mfma_f32_16x16x32_bf16 v[58:61], v[158:161], v[170:173], v[58:61]
	v_mfma_f32_16x16x32_bf16 v[46:49], v[50:53], v[178:181], v[46:49]
	v_mfma_f32_16x16x32_bf16 v[38:41], v[158:161], v[178:181], v[38:41]
	v_mfma_f32_16x16x32_bf16 v[30:33], v[50:53], v[186:189], v[30:33]
	v_mfma_f32_16x16x32_bf16 v[22:25], v[158:161], v[186:189], v[22:25]
	v_mfma_f32_16x16x32_bf16 v[14:17], v[50:53], v[194:197], v[14:17]
	v_mfma_f32_16x16x32_bf16 v[6:9], v[158:161], v[194:197], v[6:9]
	v_mfma_f32_16x16x32_bf16 v[66:69], v[146:149], v[174:177], v[66:69]
	v_mfma_f32_16x16x32_bf16 v[58:61], v[166:169], v[174:177], v[58:61]
	v_mfma_f32_16x16x32_bf16 v[46:49], v[146:149], v[182:185], v[46:49]
	v_mfma_f32_16x16x32_bf16 v[38:41], v[166:169], v[182:185], v[38:41]
	v_mfma_f32_16x16x32_bf16 v[30:33], v[146:149], v[190:193], v[30:33]
	v_mfma_f32_16x16x32_bf16 v[22:25], v[166:169], v[190:193], v[22:25]
	v_mfma_f32_16x16x32_bf16 v[14:17], v[146:149], v[198:201], v[14:17]
	v_mfma_f32_16x16x32_bf16 v[6:9], v[166:169], v[198:201], v[6:9]
	s_barrier
	s_add_u32 s24, s28, 0x40000
	s_addc_u32 s25, s29, 0
	s_mov_b32 m0, s59
	s_nop 0
	global_load_lds_dwordx4 v0, s[24:25]
	s_mov_b32 m0, s62
	s_nop 0
	global_load_lds_dwordx4 v138, s[24:25]
	s_waitcnt vmcnt(6)
	s_barrier
	v_mfma_f32_16x16x32_bf16 v[54:57], v[210:213], v[170:173], v[54:57]
	v_mfma_f32_16x16x32_bf16 v[42:45], v[202:205], v[178:181], v[42:45]
	v_mfma_f32_16x16x32_bf16 v[34:37], v[210:213], v[178:181], v[34:37]
	v_mfma_f32_16x16x32_bf16 v[26:29], v[202:205], v[186:189], v[26:29]
	v_mfma_f32_16x16x32_bf16 v[18:21], v[210:213], v[186:189], v[18:21]
	v_mfma_f32_16x16x32_bf16 v[10:13], v[202:205], v[194:197], v[10:13]
	v_mfma_f32_16x16x32_bf16 v[2:5], v[210:213], v[194:197], v[2:5]
	v_mfma_f32_16x16x32_bf16 v[50:53], v[202:205], v[170:173], v[62:65]
	v_mfma_f32_16x16x32_bf16 v[54:57], v[214:217], v[174:177], v[54:57]
	v_mfma_f32_16x16x32_bf16 v[42:45], v[206:209], v[182:185], v[42:45]
	v_mfma_f32_16x16x32_bf16 v[34:37], v[214:217], v[182:185], v[34:37]
	v_mfma_f32_16x16x32_bf16 v[26:29], v[206:209], v[190:193], v[26:29]
	v_mfma_f32_16x16x32_bf16 v[18:21], v[214:217], v[190:193], v[18:21]
	v_mfma_f32_16x16x32_bf16 v[10:13], v[206:209], v[198:201], v[10:13]
	v_mfma_f32_16x16x32_bf16 v[2:5], v[214:217], v[198:201], v[2:5]
	v_mfma_f32_16x16x32_bf16 v[50:53], v[206:209], v[174:177], v[50:53]
	v_or_b32_e32 v62, 0x18000, v155
	v_add_u32_e32 v146, 0x18400, v155
	v_add_u32_e32 v158, 0x18800, v155
	s_barrier
.Lup605_p5:
	ds_read_b128 v[62:65], v62
	ds_read_b128 v[146:149], v146
	v_add_u32_e32 v163, 0x18c00, v155
	ds_read_b128 v[158:161], v158
	ds_read_b128 v[166:169], v163
	s_add_u32 s24, s30, 0x40000
	s_addc_u32 s25, s31, 0
	s_mov_b32 m0, s7
	ds_read_b128 v[170:173], v154 offset:32768
	ds_read_b128 v[174:177], v154 offset:33792
	ds_read_b128 v[178:181], v154 offset:34816
	ds_read_b128 v[182:185], v154 offset:35840
	ds_read_b128 v[186:189], v154 offset:36864
	ds_read_b128 v[190:193], v154 offset:37888
	ds_read_b128 v[194:197], v154 offset:38912
	ds_read_b128 v[198:201], v154 offset:39936
	global_load_lds_dwordx4 v134, s[24:25]
	s_mov_b32 m0, s12
	s_nop 0
	global_load_lds_dwordx4 v136, s[24:25]
	s_barrier
	s_waitcnt lgkmcnt(0)
	s_waitcnt lgkmcnt(0)
	v_mfma_f32_16x16x32_bf16 v[130:133], v[62:65], v[170:173], v[130:133]
	v_mfma_f32_16x16x32_bf16 v[122:125], v[158:161], v[170:173], v[122:125]
	v_mfma_f32_16x16x32_bf16 v[114:117], v[62:65], v[178:181], v[114:117]
	v_mfma_f32_16x16x32_bf16 v[106:109], v[158:161], v[178:181], v[106:109]
	v_mfma_f32_16x16x32_bf16 v[98:101], v[62:65], v[186:189], v[98:101]
	v_mfma_f32_16x16x32_bf16 v[90:93], v[158:161], v[186:189], v[90:93]
	v_mfma_f32_16x16x32_bf16 v[82:85], v[62:65], v[194:197], v[82:85]
	v_mfma_f32_16x16x32_bf16 v[74:77], v[158:161], v[194:197], v[74:77]
	v_mfma_f32_16x16x32_bf16 v[130:133], v[146:149], v[174:177], v[130:133]
	v_mfma_f32_16x16x32_bf16 v[122:125], v[166:169], v[174:177], v[122:125]
	v_mfma_f32_16x16x32_bf16 v[114:117], v[146:149], v[182:185], v[114:117]
	v_mfma_f32_16x16x32_bf16 v[106:109], v[166:169], v[182:185], v[106:109]
	v_mfma_f32_16x16x32_bf16 v[98:101], v[146:149], v[190:193], v[98:101]
	v_mfma_f32_16x16x32_bf16 v[90:93], v[166:169], v[190:193], v[90:93]
	v_mfma_f32_16x16x32_bf16 v[82:85], v[146:149], v[198:201], v[82:85]
	v_mfma_f32_16x16x32_bf16 v[74:77], v[166:169], v[198:201], v[74:77]
	s_barrier
	v_or_b32_e32 v163, 0x1c000, v155
	s_mov_b32 m0, s13
	v_add_u32_e32 v165, 0x1c400, v155
	ds_read_b128 v[202:205], v163
	ds_read_b128 v[206:209], v165
	v_add_u32_e32 v163, 0x1c800, v155
	v_add_u32_e32 v165, 0x1cc00, v155
	ds_read_b128 v[210:213], v163
	ds_read_b128 v[214:217], v165
	s_add_u32 s24, s28, 0x80
	s_addc_u32 s25, s29, 0
	global_load_lds_dwordx4 v0, s[24:25]
	s_mov_b32 m0, s35
	s_nop 0
	s_add_u32 s24, s28, 0x80
	s_addc_u32 s25, s29, 0
	global_load_lds_dwordx4 v138, s[24:25]
	s_barrier
; #define PG8_STAGE(bufoff, gbase, voff) do { _Pragma("unroll") for (int _i = 0; _i < 2; ++_i) \
;     __builtin_amdgcn_global_load_lds((const unsigned*)((const char*)(gbase) + (voff)[_i]), (PG8_LAS unsigned*)(lds + (bufoff) + ldsw + _i * 8192), 16, 0, 0); } while (0)
; #define PG8_LDA(dst, b, h) do { _Pragma("unroll") for (int m = 0; m < 4; ++m) _Pragma("unroll") for (int k = 0; k < 2; ++k) dst[m][k] = *(const PG8_LAS bf16x8*)(lds + PG8_SA(b, h) + aoff + m * 2048 + k * 1024); } while (0)
; #define PG8_MMA(ai, bj, At, Bt) do { __builtin_amdgcn_s_setprio(1); _Pragma("unroll") for (int m = 0; m < 4; ++m) _Pragma("unroll") for (int n = 0; n < 2; ++n) _Pragma("unroll") for (int k = 0; k < 2; ++k) \
;     acc[ai][bj][m][n] = __builtin_amdgcn_mfma_f32_16x16x32_bf16(Bt[n][k], At[m][k], acc[ai][bj][m][n], 0, 0, 0); __builtin_amdgcn_s_setprio(0); } while (0)
; #define PG8_WAIT_V(n) asm volatile("s_waitcnt vmcnt(" #n ")" ::: "memory")
; #define PG8_WAIT_L(n) asm volatile("s_waitcnt lgkmcnt(" #n ")" ::: "memory")
; #define PG8_BAR __builtin_amdgcn_s_barrier()
; #define PG8_SCHED __builtin_amdgcn_sched_barrier(0)
; #define PG8_RTAB_LOAD(var, unit) do { if constexpr (Epi::NEEDS_R) { var = *(const uint4*)(E.ssq + (size_t)((unit).pm * BM + (tid >> 1)) * 16 + (tid & 1) * 8); } } while (0)
; template <class Epi>
; DI void gemm_phase(const bf16_t* __restrict__ gA, const bf16_t* __restrict__ gBt, int M, int N, int K, const Epi& E, char* lds_generic) {
;     ...
;       PG8_LDA(At, 1, 1); PG8_STAGE(PG8_SA(1, 0), a3, voffA);
;       PG8_BAR; PG8_WAIT_L(0); PG8_MMA(1, 0, At, B0); PG8_BAR; PG8_SCHED;
;       PG8_STAGE(PG8_SB(1, 1), b3 + hstep, voffB);
;       PG8_WAIT_V(6); PG8_BAR; PG8_MMA(1, 1, At, B1); PG8_BAR;
;     }
;     uint4 rtn_ = {0u, 0u, 0u, 0u};
;     if (has_next) PG8_RTAB_LOAD(rtn_, nxt);
	s_waitcnt lgkmcnt(0)
	s_waitcnt lgkmcnt(0)
	v_mfma_f32_16x16x32_bf16 v[126:129], v[202:205], v[170:173], v[126:129]
	v_mfma_f32_16x16x32_bf16 v[118:121], v[210:213], v[170:173], v[118:121]
	v_mfma_f32_16x16x32_bf16 v[110:113], v[202:205], v[178:181], v[110:113]
	v_mfma_f32_16x16x32_bf16 v[102:105], v[210:213], v[178:181], v[102:105]
	v_mfma_f32_16x16x32_bf16 v[94:97], v[202:205], v[186:189], v[94:97]
	v_mfma_f32_16x16x32_bf16 v[86:89], v[210:213], v[186:189], v[86:89]
	v_mfma_f32_16x16x32_bf16 v[78:81], v[202:205], v[194:197], v[78:81]
	v_mfma_f32_16x16x32_bf16 v[70:73], v[210:213], v[194:197], v[70:73]
	v_mfma_f32_16x16x32_bf16 v[126:129], v[206:209], v[174:177], v[126:129]
	v_mfma_f32_16x16x32_bf16 v[118:121], v[214:217], v[174:177], v[118:121]
	v_mfma_f32_16x16x32_bf16 v[110:113], v[206:209], v[182:185], v[110:113]
	v_mfma_f32_16x16x32_bf16 v[102:105], v[214:217], v[182:185], v[102:105]
	v_mfma_f32_16x16x32_bf16 v[94:97], v[206:209], v[190:193], v[94:97]
	v_mfma_f32_16x16x32_bf16 v[86:89], v[214:217], v[190:193], v[86:89]
	v_mfma_f32_16x16x32_bf16 v[78:81], v[206:209], v[198:201], v[78:81]
	v_mfma_f32_16x16x32_bf16 v[70:73], v[214:217], v[198:201], v[70:73]
	s_mov_b32 m0, s53
	s_barrier
	ds_read_b128 v[170:173], v154 offset:49152
	ds_read_b128 v[174:177], v154 offset:50176
	ds_read_b128 v[178:181], v154 offset:51200
	ds_read_b128 v[182:185], v154 offset:52224
	ds_read_b128 v[186:189], v154 offset:53248
	ds_read_b128 v[190:193], v154 offset:54272
	ds_read_b128 v[194:197], v154 offset:55296
	ds_read_b128 v[198:201], v154 offset:56320
	s_add_u32 s24, s30, 0x80
	s_addc_u32 s25, s31, 0
	global_load_lds_dwordx4 v134, s[24:25]
	s_mov_b32 m0, s74
	s_nop 0
	s_add_u32 s24, s30, 0x80
	s_addc_u32 s25, s31, 0
	global_load_lds_dwordx4 v136, s[24:25]
	s_barrier
	s_waitcnt lgkmcnt(0)
	s_waitcnt lgkmcnt(0)
	v_mfma_f32_16x16x32_bf16 v[66:69], v[62:65], v[170:173], v[66:69]
	v_mfma_f32_16x16x32_bf16 v[58:61], v[158:161], v[170:173], v[58:61]
	v_mfma_f32_16x16x32_bf16 v[46:49], v[62:65], v[178:181], v[46:49]
	v_mfma_f32_16x16x32_bf16 v[38:41], v[158:161], v[178:181], v[38:41]
	v_mfma_f32_16x16x32_bf16 v[30:33], v[62:65], v[186:189], v[30:33]
	v_mfma_f32_16x16x32_bf16 v[22:25], v[158:161], v[186:189], v[22:25]
	v_mfma_f32_16x16x32_bf16 v[14:17], v[62:65], v[194:197], v[14:17]
	v_mfma_f32_16x16x32_bf16 v[6:9], v[158:161], v[194:197], v[6:9]
	v_mfma_f32_16x16x32_bf16 v[66:69], v[146:149], v[174:177], v[66:69]
	v_mfma_f32_16x16x32_bf16 v[58:61], v[166:169], v[174:177], v[58:61]
	v_mfma_f32_16x16x32_bf16 v[46:49], v[146:149], v[182:185], v[46:49]
	v_mfma_f32_16x16x32_bf16 v[38:41], v[166:169], v[182:185], v[38:41]
	v_mfma_f32_16x16x32_bf16 v[30:33], v[146:149], v[190:193], v[30:33]
	v_mfma_f32_16x16x32_bf16 v[22:25], v[166:169], v[190:193], v[22:25]
	v_mfma_f32_16x16x32_bf16 v[14:17], v[146:149], v[198:201], v[14:17]
	v_mfma_f32_16x16x32_bf16 v[6:9], v[166:169], v[198:201], v[6:9]
	s_barrier
	s_add_u32 s24, s28, 0x40080
	s_addc_u32 s25, s29, 0
	s_mov_b32 m0, s60
	s_nop 0
	global_load_lds_dwordx4 v0, s[24:25]
	s_mov_b32 m0, s6
	s_nop 0
	global_load_lds_dwordx4 v138, s[24:25]
	s_waitcnt vmcnt(6)
	s_barrier
	v_mfma_f32_16x16x32_bf16 v[50:53], v[202:205], v[170:173], v[50:53]
	v_mfma_f32_16x16x32_bf16 v[62:65], v[206:209], v[174:177], v[50:53]
	v_mfma_f32_16x16x32_bf16 v[50:53], v[210:213], v[170:173], v[54:57]
	v_mfma_f32_16x16x32_bf16 v[42:45], v[202:205], v[178:181], v[42:45]
	v_mfma_f32_16x16x32_bf16 v[34:37], v[210:213], v[178:181], v[34:37]
	v_mfma_f32_16x16x32_bf16 v[26:29], v[202:205], v[186:189], v[26:29]
	v_mfma_f32_16x16x32_bf16 v[18:21], v[210:213], v[186:189], v[18:21]
	v_mfma_f32_16x16x32_bf16 v[10:13], v[202:205], v[194:197], v[10:13]
	v_mfma_f32_16x16x32_bf16 v[2:5], v[210:213], v[194:197], v[2:5]
	v_mfma_f32_16x16x32_bf16 v[54:57], v[214:217], v[174:177], v[50:53]
	v_mfma_f32_16x16x32_bf16 v[42:45], v[206:209], v[182:185], v[42:45]
	v_mfma_f32_16x16x32_bf16 v[34:37], v[214:217], v[182:185], v[34:37]
	v_mfma_f32_16x16x32_bf16 v[26:29], v[206:209], v[190:193], v[26:29]
	v_mfma_f32_16x16x32_bf16 v[18:21], v[214:217], v[190:193], v[18:21]
	v_mfma_f32_16x16x32_bf16 v[10:13], v[206:209], v[198:201], v[10:13]
	v_mfma_f32_16x16x32_bf16 v[2:5], v[214:217], v[198:201], v[2:5]
	s_add_i32 s23, s23, 2
	s_add_u32 vcc_lo, vcc_lo, 0x100
	s_addc_u32 vcc_hi, vcc_hi, 0
	s_add_u32 s87, s87, 0x100
	s_addc_u32 s22, s22, 0
	s_cmp_gt_u32 s23, 13
	s_barrier
	s_cbranch_scc0 .LBB0_605
	v_mov_b32_e32 v50, 0
	s_and_b64 vcc, exec, s[38:39]
	v_mov_b32_e32 v51, 0
	v_mov_b32_e32 v52, 0
	v_mov_b32_e32 v53, 0
	s_cbranch_vccz .LBB0_608
	v_lshl_add_u32 v50, s86, 8, v150
	v_ashrrev_i32_e32 v51, 31, v50
	v_lshlrev_b64 v[50:51], 5, v[50:51]
	v_lshl_add_u64 v[50:51], v[140:141], 0, v[50:51]
	global_load_dwordx4 v[50:53], v[50:51], off

; #define PG8_STAGE(bufoff, gbase, voff) do { _Pragma("unroll") for (int _i = 0; _i < 2; ++_i) \
;     __builtin_amdgcn_global_load_lds((const unsigned*)((const char*)(gbase) + (voff)[_i]), (PG8_LAS unsigned*)(lds + (bufoff) + ldsw + _i * 8192), 16, 0, 0); } while (0)
; #define PG8_LDA(dst, b, h) do { _Pragma("unroll") for (int m = 0; m < 4; ++m) _Pragma("unroll") for (int k = 0; k < 2; ++k) dst[m][k] = *(const PG8_LAS bf16x8*)(lds + PG8_SA(b, h) + aoff + m * 2048 + k * 1024); } while (0)
; #define PG8_LDB(dst, b, h) do { _Pragma("unroll") for (int n = 0; n < 2; ++n) _Pragma("unroll") for (int k = 0; k < 2; ++k) dst[n][k] = *(const PG8_LAS bf16x8*)(lds + PG8_SB(b, h) + boff + n * 2048 + k * 1024); } while (0)
; #define PG8_MMA(ai, bj, At, Bt) do { __builtin_amdgcn_s_setprio(1); _Pragma("unroll") for (int m = 0; m < 4; ++m) _Pragma("unroll") for (int n = 0; n < 2; ++n) _Pragma("unroll") for (int k = 0; k < 2; ++k) \
;     acc[ai][bj][m][n] = __builtin_amdgcn_mfma_f32_16x16x32_bf16(Bt[n][k], At[m][k], acc[ai][bj][m][n], 0, 0, 0); __builtin_amdgcn_s_setprio(0); } while (0)
; #define PG8_WAIT_V(n) asm volatile("s_waitcnt vmcnt(" #n ")" ::: "memory")
; #define PG8_WAIT_L(n) asm volatile("s_waitcnt lgkmcnt(" #n ")" ::: "memory")
; #define PG8_BAR __builtin_amdgcn_s_barrier()
; #define PG8_SCHED __builtin_amdgcn_sched_barrier(0)
; template <class Epi>
; DI void gemm_phase(const bf16_t* __restrict__ gA, const bf16_t* __restrict__ gBt, int M, int N, int K, const Epi& E, char* lds_generic) {
;     ...
;       const bool last = (t == nt - 2);
;       const char* a1 = cA + (size_t)(t + 1) * kstep;
;       const char* a2 = last ? nA : cA + (size_t)(t + 2) * kstep; const char* b2 = last ? nB : cB + (size_t)(t + 2) * kstep;
;       const char* a3 = a2 + kstep; const char* b3 = b2 + kstep;
;       PG8_LDB(B0, 0, 0); PG8_SCHED; PG8_LDA(At, 0, 0); PG8_STAGE(PG8_SA(1, 1), a1 + hstep, voffA);
;       PG8_WAIT_L(8); PG8_BAR; PG8_WAIT_L(0); PG8_MMA(0, 0, At, B0); PG8_BAR; PG8_SCHED;
;       PG8_LDB(B1, 0, 1); PG8_STAGE(PG8_SB(0, 0), b2, voffB);
;       PG8_BAR; PG8_WAIT_L(0); PG8_MMA(0, 1, At, B1); PG8_BAR;
;       PG8_LDA(At, 0, 1); PG8_STAGE(PG8_SA(0, 0), a2, voffA);
;       PG8_BAR; PG8_WAIT_L(0); PG8_MMA(1, 0, At, B0); PG8_BAR; PG8_SCHED;
;       PG8_STAGE(PG8_SB(0, 1), b2 + hstep, voffB);
;       PG8_WAIT_V(6); PG8_BAR; PG8_MMA(1, 1, At, B1); PG8_BAR;
.LBB0_684:
	v_or_b32_e32 v140, 0x10000, v146
	v_add_u32_e32 v148, 0x10400, v146
	v_add_u32_e32 v152, 0x10800, v146
	v_add_u32_e32 v156, 0x10c00, v146
	ds_read_b128 v[140:143], v140
	ds_read_b128 v[148:151], v148
	ds_read_b128 v[152:155], v152
	ds_read_b128 v[156:159], v156
	s_add_u32 s28, s88, 0x100
	s_addc_u32 s29, s89, 0
	s_cmp_eq_u32 s23, 40
	s_cselect_b32 s91, s87, s29
	s_cselect_b32 s90, s86, s28
	s_cselect_b32 s31, s1, s22
	s_cselect_b32 s30, s0, s21
	s_add_i32 m0, s12, 0xc000
	ds_read_b128 v[166:169], v145
	ds_read_b128 v[170:173], v145 offset:1024
	ds_read_b128 v[174:177], v145 offset:2048
	ds_read_b128 v[178:181], v145 offset:3072
	ds_read_b128 v[182:185], v145 offset:4096
	ds_read_b128 v[186:189], v145 offset:5120
	ds_read_b128 v[190:193], v145 offset:6144
	ds_read_b128 v[194:197], v145 offset:7168
	global_load_lds_dwordx4 v136, s[88:89]
	s_add_i32 m0, s12, 0xe000
	s_nop 0
	global_load_lds_dwordx4 v138, s[88:89]
	s_barrier
	s_waitcnt lgkmcnt(0)
	s_waitcnt lgkmcnt(0)
	v_mfma_f32_16x16x32_bf16 v[126:129], v[140:143], v[166:169], v[126:129]
	v_mfma_f32_16x16x32_bf16 v[122:125], v[152:155], v[166:169], v[122:125]
	v_mfma_f32_16x16x32_bf16 v[110:113], v[140:143], v[174:177], v[110:113]
	v_mfma_f32_16x16x32_bf16 v[106:109], v[152:155], v[174:177], v[106:109]
	v_mfma_f32_16x16x32_bf16 v[94:97], v[140:143], v[182:185], v[94:97]
	v_mfma_f32_16x16x32_bf16 v[90:93], v[152:155], v[182:185], v[90:93]
	v_mfma_f32_16x16x32_bf16 v[78:81], v[140:143], v[190:193], v[78:81]
	v_mfma_f32_16x16x32_bf16 v[74:77], v[152:155], v[190:193], v[74:77]
	v_mfma_f32_16x16x32_bf16 v[126:129], v[148:151], v[170:173], v[126:129]
	v_mfma_f32_16x16x32_bf16 v[122:125], v[156:159], v[170:173], v[122:125]
	v_mfma_f32_16x16x32_bf16 v[110:113], v[148:151], v[178:181], v[110:113]
	v_mfma_f32_16x16x32_bf16 v[106:109], v[156:159], v[178:181], v[106:109]
	v_mfma_f32_16x16x32_bf16 v[94:97], v[148:151], v[186:189], v[94:97]
	v_mfma_f32_16x16x32_bf16 v[90:93], v[156:159], v[186:189], v[90:93]
	v_mfma_f32_16x16x32_bf16 v[78:81], v[148:151], v[194:197], v[78:81]
	v_mfma_f32_16x16x32_bf16 v[74:77], v[156:159], v[194:197], v[74:77]
	s_barrier
	v_or_b32_e32 v160, 0x14000, v146
	v_add_u32_e32 v161, 0x14400, v146
	ds_read_b128 v[198:201], v160
	ds_read_b128 v[202:205], v161
	v_add_u32_e32 v160, 0x14800, v146
	v_add_u32_e32 v161, 0x14c00, v146
	s_mov_b32 m0, s13
	ds_read_b128 v[206:209], v160
	ds_read_b128 v[210:213], v161
	global_load_lds_dwordx4 v0, s[30:31]
	s_mov_b32 m0, s14
	s_nop 0
	global_load_lds_dwordx4 v134, s[30:31]
	s_barrier
	s_waitcnt lgkmcnt(0)
	s_waitcnt lgkmcnt(0)
	v_mfma_f32_16x16x32_bf16 v[118:121], v[198:201], v[166:169], v[118:121]
	v_mfma_f32_16x16x32_bf16 v[114:117], v[206:209], v[166:169], v[114:117]
	v_mfma_f32_16x16x32_bf16 v[102:105], v[198:201], v[174:177], v[102:105]
	v_mfma_f32_16x16x32_bf16 v[98:101], v[206:209], v[174:177], v[98:101]
	v_mfma_f32_16x16x32_bf16 v[86:89], v[198:201], v[182:185], v[86:89]
	v_mfma_f32_16x16x32_bf16 v[82:85], v[206:209], v[182:185], v[82:85]
	v_mfma_f32_16x16x32_bf16 v[70:73], v[198:201], v[190:193], v[70:73]
	v_mfma_f32_16x16x32_bf16 v[66:69], v[206:209], v[190:193], v[66:69]
	v_mfma_f32_16x16x32_bf16 v[118:121], v[202:205], v[170:173], v[118:121]
	v_mfma_f32_16x16x32_bf16 v[114:117], v[210:213], v[170:173], v[114:117]
	v_mfma_f32_16x16x32_bf16 v[102:105], v[202:205], v[178:181], v[102:105]
	v_mfma_f32_16x16x32_bf16 v[98:101], v[210:213], v[178:181], v[98:101]
	v_mfma_f32_16x16x32_bf16 v[86:89], v[202:205], v[186:189], v[86:89]
	v_mfma_f32_16x16x32_bf16 v[82:85], v[210:213], v[186:189], v[82:85]
	v_mfma_f32_16x16x32_bf16 v[70:73], v[202:205], v[194:197], v[70:73]
	v_mfma_f32_16x16x32_bf16 v[66:69], v[210:213], v[194:197], v[66:69]
	s_mov_b32 m0, s12
	s_barrier
	ds_read_b128 v[166:169], v145 offset:16384
	ds_read_b128 v[170:173], v145 offset:17408
	ds_read_b128 v[174:177], v145 offset:18432
	ds_read_b128 v[178:181], v145 offset:19456
	ds_read_b128 v[182:185], v145 offset:20480
	ds_read_b128 v[186:189], v145 offset:21504
	ds_read_b128 v[190:193], v145 offset:22528
	ds_read_b128 v[194:197], v145 offset:23552
	global_load_lds_dwordx4 v130, s[90:91]
	s_mov_b32 m0, s15
	s_nop 0
	global_load_lds_dwordx4 v132, s[90:91]
	s_barrier
	s_waitcnt lgkmcnt(0)
	s_waitcnt lgkmcnt(0)
	v_mfma_f32_16x16x32_bf16 v[62:65], v[140:143], v[166:169], v[62:65]
	v_mfma_f32_16x16x32_bf16 v[58:61], v[152:155], v[166:169], v[58:61]
	v_mfma_f32_16x16x32_bf16 v[46:49], v[140:143], v[174:177], v[46:49]
	v_mfma_f32_16x16x32_bf16 v[42:45], v[152:155], v[174:177], v[42:45]
	v_mfma_f32_16x16x32_bf16 v[30:33], v[140:143], v[182:185], v[30:33]
	v_mfma_f32_16x16x32_bf16 v[26:29], v[152:155], v[182:185], v[26:29]
	v_mfma_f32_16x16x32_bf16 v[14:17], v[140:143], v[190:193], v[14:17]
	v_mfma_f32_16x16x32_bf16 v[10:13], v[152:155], v[190:193], v[10:13]
	v_mfma_f32_16x16x32_bf16 v[62:65], v[148:151], v[170:173], v[62:65]
	v_mfma_f32_16x16x32_bf16 v[58:61], v[156:159], v[170:173], v[58:61]
	v_mfma_f32_16x16x32_bf16 v[46:49], v[148:151], v[178:181], v[46:49]
	v_mfma_f32_16x16x32_bf16 v[42:45], v[156:159], v[178:181], v[42:45]
	v_mfma_f32_16x16x32_bf16 v[30:33], v[148:151], v[186:189], v[30:33]
	v_mfma_f32_16x16x32_bf16 v[26:29], v[156:159], v[186:189], v[26:29]
	v_mfma_f32_16x16x32_bf16 v[14:17], v[148:151], v[194:197], v[14:17]
	v_mfma_f32_16x16x32_bf16 v[10:13], v[156:159], v[194:197], v[10:13]
	s_barrier
	s_add_u32 s24, s30, 0xb0000
	s_addc_u32 s25, s31, 0
	s_mov_b32 m0, s18
	s_nop 0
	global_load_lds_dwordx4 v0, s[24:25]
	s_mov_b32 m0, s35
	s_nop 0
	global_load_lds_dwordx4 v134, s[24:25]
	s_waitcnt vmcnt(6)
	s_barrier
; #define PG8_STAGE(bufoff, gbase, voff) do { _Pragma("unroll") for (int _i = 0; _i < 2; ++_i) \
;     __builtin_amdgcn_global_load_lds((const unsigned*)((const char*)(gbase) + (voff)[_i]), (PG8_LAS unsigned*)(lds + (bufoff) + ldsw + _i * 8192), 16, 0, 0); } while (0)
; #define PG8_LDA(dst, b, h) do { _Pragma("unroll") for (int m = 0; m < 4; ++m) _Pragma("unroll") for (int k = 0; k < 2; ++k) dst[m][k] = *(const PG8_LAS bf16x8*)(lds + PG8_SA(b, h) + aoff + m * 2048 + k * 1024); } while (0)
; #define PG8_LDB(dst, b, h) do { _Pragma("unroll") for (int n = 0; n < 2; ++n) _Pragma("unroll") for (int k = 0; k < 2; ++k) dst[n][k] = *(const PG8_LAS bf16x8*)(lds + PG8_SB(b, h) + boff + n * 2048 + k * 1024); } while (0)
; #define PG8_MMA(ai, bj, At, Bt) do { __builtin_amdgcn_s_setprio(1); _Pragma("unroll") for (int m = 0; m < 4; ++m) _Pragma("unroll") for (int n = 0; n < 2; ++n) _Pragma("unroll") for (int k = 0; k < 2; ++k) \
;     acc[ai][bj][m][n] = __builtin_amdgcn_mfma_f32_16x16x32_bf16(Bt[n][k], At[m][k], acc[ai][bj][m][n], 0, 0, 0); __builtin_amdgcn_s_setprio(0); } while (0)
; #define PG8_WAIT_V(n) asm volatile("s_waitcnt vmcnt(" #n ")" ::: "memory")
; #define PG8_WAIT_L(n) asm volatile("s_waitcnt lgkmcnt(" #n ")" ::: "memory")
; #define PG8_BAR __builtin_amdgcn_s_barrier()
; #define PG8_SCHED __builtin_amdgcn_sched_barrier(0)
; template <class Epi>
; DI void gemm_phase(const bf16_t* __restrict__ gA, const bf16_t* __restrict__ gBt, int M, int N, int K, const Epi& E, char* lds_generic) {
;     ...
;       PG8_WAIT_V(6); PG8_BAR; PG8_MMA(1, 1, At, B1); PG8_BAR;
;       PG8_LDB(B0, 1, 0); PG8_SCHED; PG8_LDA(At, 1, 0); PG8_STAGE(PG8_SA(0, 1), a2 + hstep, voffA);
;       PG8_WAIT_L(8); PG8_BAR; PG8_WAIT_L(0); PG8_MMA(0, 0, At, B0); PG8_BAR; PG8_SCHED;
;       PG8_LDB(B1, 1, 1); PG8_STAGE(PG8_SB(1, 0), b3, voffB);
;       PG8_BAR; PG8_WAIT_L(0); PG8_MMA(0, 1, At, B1); PG8_BAR;
;       PG8_LDA(At, 1, 1); PG8_STAGE(PG8_SA(1, 0), a3, voffA);
	v_mfma_f32_16x16x32_bf16 v[54:57], v[198:201], v[166:169], v[54:57]
	v_mfma_f32_16x16x32_bf16 v[50:53], v[206:209], v[166:169], v[50:53]
	v_mfma_f32_16x16x32_bf16 v[38:41], v[198:201], v[174:177], v[38:41]
	v_mfma_f32_16x16x32_bf16 v[34:37], v[206:209], v[174:177], v[34:37]
	v_mfma_f32_16x16x32_bf16 v[22:25], v[198:201], v[182:185], v[22:25]
	v_mfma_f32_16x16x32_bf16 v[18:21], v[206:209], v[182:185], v[18:21]
	v_mfma_f32_16x16x32_bf16 v[6:9], v[198:201], v[190:193], v[6:9]
	v_mfma_f32_16x16x32_bf16 v[2:5], v[206:209], v[190:193], v[2:5]
	v_mfma_f32_16x16x32_bf16 v[54:57], v[202:205], v[170:173], v[54:57]
	v_mfma_f32_16x16x32_bf16 v[50:53], v[210:213], v[170:173], v[50:53]
	v_mfma_f32_16x16x32_bf16 v[38:41], v[202:205], v[178:181], v[38:41]
	v_mfma_f32_16x16x32_bf16 v[34:37], v[210:213], v[178:181], v[34:37]
	v_mfma_f32_16x16x32_bf16 v[22:25], v[202:205], v[186:189], v[22:25]
	v_mfma_f32_16x16x32_bf16 v[18:21], v[210:213], v[186:189], v[18:21]
	v_mfma_f32_16x16x32_bf16 v[6:9], v[202:205], v[194:197], v[6:9]
	v_mfma_f32_16x16x32_bf16 v[2:5], v[210:213], v[194:197], v[2:5]
	v_or_b32_e32 v140, 0x18000, v146
	v_add_u32_e32 v148, 0x18400, v146
	v_add_u32_e32 v152, 0x18800, v146
	v_add_u32_e32 v156, 0x18c00, v146
	s_barrier
	ds_read_b128 v[140:143], v140
	ds_read_b128 v[148:151], v148
	ds_read_b128 v[152:155], v152
	ds_read_b128 v[156:159], v156
	s_add_u32 s24, s90, 0xb0000
	s_addc_u32 s25, s91, 0
	s_mov_b32 m0, s53
	ds_read_b128 v[166:169], v145 offset:32768
	ds_read_b128 v[170:173], v145 offset:33792
	ds_read_b128 v[174:177], v145 offset:34816
	ds_read_b128 v[178:181], v145 offset:35840
	ds_read_b128 v[182:185], v145 offset:36864
	ds_read_b128 v[186:189], v145 offset:37888
	ds_read_b128 v[190:193], v145 offset:38912
	ds_read_b128 v[194:197], v145 offset:39936
	global_load_lds_dwordx4 v130, s[24:25]
	s_mov_b32 m0, s58
	s_nop 0
	global_load_lds_dwordx4 v132, s[24:25]
	s_barrier
	s_waitcnt lgkmcnt(0)
	s_waitcnt lgkmcnt(0)
	v_mfma_f32_16x16x32_bf16 v[126:129], v[140:143], v[166:169], v[126:129]
	v_mfma_f32_16x16x32_bf16 v[122:125], v[152:155], v[166:169], v[122:125]
	v_mfma_f32_16x16x32_bf16 v[110:113], v[140:143], v[174:177], v[110:113]
	v_mfma_f32_16x16x32_bf16 v[106:109], v[152:155], v[174:177], v[106:109]
	v_mfma_f32_16x16x32_bf16 v[94:97], v[140:143], v[182:185], v[94:97]
	v_mfma_f32_16x16x32_bf16 v[90:93], v[152:155], v[182:185], v[90:93]
	v_mfma_f32_16x16x32_bf16 v[78:81], v[140:143], v[190:193], v[78:81]
	v_mfma_f32_16x16x32_bf16 v[74:77], v[152:155], v[190:193], v[74:77]
	v_mfma_f32_16x16x32_bf16 v[126:129], v[148:151], v[170:173], v[126:129]
	v_mfma_f32_16x16x32_bf16 v[122:125], v[156:159], v[170:173], v[122:125]
	v_mfma_f32_16x16x32_bf16 v[110:113], v[148:151], v[178:181], v[110:113]
	v_mfma_f32_16x16x32_bf16 v[106:109], v[156:159], v[178:181], v[106:109]
	v_mfma_f32_16x16x32_bf16 v[94:97], v[148:151], v[186:189], v[94:97]
	v_mfma_f32_16x16x32_bf16 v[90:93], v[156:159], v[186:189], v[90:93]
	v_mfma_f32_16x16x32_bf16 v[78:81], v[148:151], v[194:197], v[78:81]
	v_mfma_f32_16x16x32_bf16 v[74:77], v[156:159], v[194:197], v[74:77]
	s_barrier
	v_or_b32_e32 v163, 0x1c000, v146
	s_mov_b32 m0, s59
	v_add_u32_e32 v165, 0x1c400, v146
	ds_read_b128 v[198:201], v163
	ds_read_b128 v[202:205], v165
	v_add_u32_e32 v163, 0x1c800, v146
	v_add_u32_e32 v165, 0x1cc00, v146
	ds_read_b128 v[206:209], v163
	ds_read_b128 v[210:213], v165
	s_add_u32 s24, s30, 0x80
	s_addc_u32 s25, s31, 0
	global_load_lds_dwordx4 v0, s[24:25]
	s_mov_b32 m0, s60
	s_nop 0
	s_add_u32 s24, s30, 0x80
	s_addc_u32 s25, s31, 0
	global_load_lds_dwordx4 v134, s[24:25]
	s_barrier
	s_waitcnt lgkmcnt(0)
	s_waitcnt lgkmcnt(0)
	v_mfma_f32_16x16x32_bf16 v[118:121], v[198:201], v[166:169], v[118:121]
	v_mfma_f32_16x16x32_bf16 v[114:117], v[206:209], v[166:169], v[114:117]
	v_mfma_f32_16x16x32_bf16 v[102:105], v[198:201], v[174:177], v[102:105]
	v_mfma_f32_16x16x32_bf16 v[98:101], v[206:209], v[174:177], v[98:101]
	v_mfma_f32_16x16x32_bf16 v[86:89], v[198:201], v[182:185], v[86:89]
	v_mfma_f32_16x16x32_bf16 v[82:85], v[206:209], v[182:185], v[82:85]
	v_mfma_f32_16x16x32_bf16 v[70:73], v[198:201], v[190:193], v[70:73]
	v_mfma_f32_16x16x32_bf16 v[66:69], v[206:209], v[190:193], v[66:69]
	v_mfma_f32_16x16x32_bf16 v[118:121], v[202:205], v[170:173], v[118:121]
	v_mfma_f32_16x16x32_bf16 v[114:117], v[210:213], v[170:173], v[114:117]
	v_mfma_f32_16x16x32_bf16 v[102:105], v[202:205], v[178:181], v[102:105]
	v_mfma_f32_16x16x32_bf16 v[98:101], v[210:213], v[178:181], v[98:101]
	v_mfma_f32_16x16x32_bf16 v[86:89], v[202:205], v[186:189], v[86:89]
	v_mfma_f32_16x16x32_bf16 v[82:85], v[210:213], v[186:189], v[82:85]
	v_mfma_f32_16x16x32_bf16 v[70:73], v[202:205], v[194:197], v[70:73]
	v_mfma_f32_16x16x32_bf16 v[66:69], v[210:213], v[194:197], v[66:69]
	s_mov_b32 m0, s62
	s_barrier
	ds_read_b128 v[166:169], v145 offset:49152
	ds_read_b128 v[170:173], v145 offset:50176
	ds_read_b128 v[174:177], v145 offset:51200
	ds_read_b128 v[178:181], v145 offset:52224
	ds_read_b128 v[182:185], v145 offset:53248
	ds_read_b128 v[186:189], v145 offset:54272
	ds_read_b128 v[190:193], v145 offset:55296
	ds_read_b128 v[194:197], v145 offset:56320
	s_add_u32 s24, s90, 0x80
	s_addc_u32 s25, s91, 0
	global_load_lds_dwordx4 v130, s[24:25]
	s_mov_b32 m0, s72
	s_nop 0
	s_add_u32 s24, s90, 0x80
	s_addc_u32 s25, s91, 0
	global_load_lds_dwordx4 v132, s[24:25]
	s_barrier
; DI bf16_t f2bf(float x) { unsigned u = __float_as_uint(x); u += 0x7fffu + ((u >> 16) & 1u); return (bf16_t)(u >> 16); }
; DI unsigned pack2(float lo, float hi) { f32x2_t v = {lo, hi}; return __builtin_bit_cast(unsigned, __builtin_convertvector(v, bf16x2_t)); }
; #define PG8_LAS __attribute__((address_space(3)))
; #define PG8_STAGE(bufoff, gbase, voff) do { _Pragma("unroll") for (int _i = 0; _i < 2; ++_i) \
;     __builtin_amdgcn_global_load_lds((const unsigned*)((const char*)(gbase) + (voff)[_i]), (PG8_LAS unsigned*)(lds + (bufoff) + ldsw + _i * 8192), 16, 0, 0); } while (0)
; #define PG8_WAIT_V(n) asm volatile("s_waitcnt vmcnt(" #n ")" ::: "memory")
; #define PG8_WAIT_L(n) asm volatile("s_waitcnt lgkmcnt(" #n ")" ::: "memory")
; #define PG8_BAR __builtin_amdgcn_s_barrier()
; #define PG8_SCHED __builtin_amdgcn_sched_barrier(0)
;   DI void operator()(const f32x4 (&acc)[2][2][4][2], const Unit& u, int wr, int wc, int fr, int fq, const PG8_LAS float*) const {
;     const int row0 = u.pm * BM + wr * 64 + fr, col0 = u.pn * BM + wc * 32 + 8 * fq;
; #pragma unroll
;     for (int ai = 0; ai < 2; ++ai)
; #pragma unroll
;       for (int m = 0; m < 4; ++m) { const int row = row0 + ai * HALF + m * 16; bf16_t* rowp = dst + (size_t)row * DM + col0; float ss = 0.f;
; #pragma unroll
;         for (int bj = 0; bj < 2; ++bj) { const f32x4 v0 = acc[ai][bj][m][0] * coef, v1 = acc[ai][bj][m][1] * coef;
;           ss += v0[0] * v0[0] + v0[1] * v0[1] + v0[2] * v0[2] + v0[3] * v0[3] + v1[0] * v1[0] + v1[1] * v1[1] + v1[2] * v1[2] + v1[3] * v1[3];
;           u32x4 w; w.x = pack2(v0[0], v0[1]); w.y = pack2(v0[2], v0[3]); w.z = pack2(v1[0], v1[1]); w.w = pack2(v1[2], v1[3]);
;           *(u32x4*)(rowp + bj * HALF) = w; }
;         ss += __shfl_xor(ss, 16); ss += __shfl_xor(ss, 32);
;         if (fq == 0) ssq[(size_t)row * 16 + u.pn * 4 + wc] = f2bf(ss); }
; template <class Epi>
; DI void gemm_phase(const bf16_t* __restrict__ gA, const bf16_t* __restrict__ gBt, int M, int N, int K, const Epi& E, char* lds_generic) {
;     ...
;       PG8_BAR; PG8_WAIT_L(0); PG8_MMA(1, 0, At, B0); PG8_BAR; PG8_SCHED;
;       PG8_STAGE(PG8_SB(1, 1), b3 + hstep, voffB);
;       PG8_WAIT_V(6); PG8_BAR; PG8_MMA(1, 1, At, B1); PG8_BAR;
;     }
;     uint4 rtn_ = {0u, 0u, 0u, 0u};
;     if (has_next) PG8_RTAB_LOAD(rtn_, nxt);
;     E(acc, cur, wr, wc, fr, fq, (const PG8_LAS float*)(lds + RT_OFF) + (ui & 1) * 256);
	s_waitcnt lgkmcnt(0)
	s_waitcnt lgkmcnt(0)
	v_mfma_f32_16x16x32_bf16 v[62:65], v[140:143], v[166:169], v[62:65]
	v_mfma_f32_16x16x32_bf16 v[58:61], v[152:155], v[166:169], v[58:61]
	v_mfma_f32_16x16x32_bf16 v[46:49], v[140:143], v[174:177], v[46:49]
	v_mfma_f32_16x16x32_bf16 v[42:45], v[152:155], v[174:177], v[42:45]
	v_mfma_f32_16x16x32_bf16 v[30:33], v[140:143], v[182:185], v[30:33]
	v_mfma_f32_16x16x32_bf16 v[26:29], v[152:155], v[182:185], v[26:29]
	v_mfma_f32_16x16x32_bf16 v[14:17], v[140:143], v[190:193], v[14:17]
	v_mfma_f32_16x16x32_bf16 v[10:13], v[152:155], v[190:193], v[10:13]
	v_mfma_f32_16x16x32_bf16 v[62:65], v[148:151], v[170:173], v[62:65]
	v_mfma_f32_16x16x32_bf16 v[58:61], v[156:159], v[170:173], v[58:61]
	v_mfma_f32_16x16x32_bf16 v[46:49], v[148:151], v[178:181], v[46:49]
	v_mfma_f32_16x16x32_bf16 v[42:45], v[156:159], v[178:181], v[42:45]
	v_mfma_f32_16x16x32_bf16 v[30:33], v[148:151], v[186:189], v[30:33]
	v_mfma_f32_16x16x32_bf16 v[26:29], v[156:159], v[186:189], v[26:29]
	v_mfma_f32_16x16x32_bf16 v[14:17], v[148:151], v[194:197], v[14:17]
	v_mfma_f32_16x16x32_bf16 v[10:13], v[156:159], v[194:197], v[10:13]
	s_barrier
	s_add_u32 s24, s30, 0xb0080
	s_addc_u32 s25, s31, 0
	s_mov_b32 m0, s74
	s_nop 0
	global_load_lds_dwordx4 v0, s[24:25]
	s_mov_b32 m0, s19
	s_nop 0
	global_load_lds_dwordx4 v134, s[24:25]
	s_waitcnt vmcnt(6)
	s_barrier
	v_mfma_f32_16x16x32_bf16 v[54:57], v[198:201], v[166:169], v[54:57]
	v_mfma_f32_16x16x32_bf16 v[50:53], v[206:209], v[166:169], v[50:53]
	v_mfma_f32_16x16x32_bf16 v[38:41], v[198:201], v[174:177], v[38:41]
	v_mfma_f32_16x16x32_bf16 v[34:37], v[206:209], v[174:177], v[34:37]
	v_mfma_f32_16x16x32_bf16 v[22:25], v[198:201], v[182:185], v[22:25]
	v_mfma_f32_16x16x32_bf16 v[18:21], v[206:209], v[182:185], v[18:21]
	v_mfma_f32_16x16x32_bf16 v[6:9], v[198:201], v[190:193], v[6:9]
	v_mfma_f32_16x16x32_bf16 v[2:5], v[206:209], v[190:193], v[2:5]
	v_mfma_f32_16x16x32_bf16 v[54:57], v[202:205], v[170:173], v[54:57]
	v_mfma_f32_16x16x32_bf16 v[50:53], v[210:213], v[170:173], v[50:53]
	v_mfma_f32_16x16x32_bf16 v[38:41], v[202:205], v[178:181], v[38:41]
	v_mfma_f32_16x16x32_bf16 v[34:37], v[210:213], v[178:181], v[34:37]
	v_mfma_f32_16x16x32_bf16 v[22:25], v[202:205], v[186:189], v[22:25]
	v_mfma_f32_16x16x32_bf16 v[18:21], v[210:213], v[186:189], v[18:21]
	v_mfma_f32_16x16x32_bf16 v[6:9], v[202:205], v[194:197], v[6:9]
	v_mfma_f32_16x16x32_bf16 v[2:5], v[210:213], v[194:197], v[2:5]
	s_add_i32 s23, s23, 2
	s_add_u32 s21, s21, 0x100
	s_addc_u32 s22, s22, 0
	s_cmp_gt_u32 s23, 41
	s_mov_b64 s[88:89], s[28:29]
	s_barrier
	s_cbranch_scc0 .LBB0_684
	v_pk_mul_f32 v[126:127], v[126:127], 0.5 op_sel_hi:[1,0]
	v_pk_mul_f32 v[128:129], v[128:129], 0.5 op_sel_hi:[1,0]
	v_mul_f32_e32 v154, v127, v127
	v_fmac_f32_e32 v154, v126, v126
	v_fmac_f32_e32 v154, v128, v128
	v_pk_mul_f32 v[118:119], v[118:119], 0.5 op_sel_hi:[1,0]
	v_pk_mul_f32 v[152:153], v[124:125], 0.5 op_sel_hi:[1,0]
	v_pk_mul_f32 v[124:125], v[122:123], 0.5 op_sel_hi:[1,0]
	v_fmac_f32_e32 v154, v129, v129
	v_cvt_pk_bf16_f32 v123, v128, v129
	v_pk_mul_f32 v[128:129], v[114:115], 0.5 op_sel_hi:[1,0]
	v_mul_f32_e32 v114, v119, v119
	v_pk_mul_f32 v[120:121], v[120:121], 0.5 op_sel_hi:[1,0]
	v_fmac_f32_e32 v114, v118, v118
	v_fmac_f32_e32 v114, v120, v120
	v_fmac_f32_e32 v114, v121, v121
	v_fmac_f32_e32 v154, v124, v124
	v_fmac_f32_e32 v114, v128, v128
	v_xor_b32_e32 v143, 16, v223
	v_fmac_f32_e32 v154, v125, v125
	v_cvt_pk_bf16_f32 v122, v126, v127
	v_pk_mul_f32 v[126:127], v[116:117], 0.5 op_sel_hi:[1,0]
	v_fmac_f32_e32 v114, v129, v129
	v_cmp_lt_i32_e32 vcc, v143, v225
	v_fmac_f32_e32 v154, v152, v152
	v_fmac_f32_e32 v114, v126, v126
	v_cndmask_b32_e32 v143, v223, v143, vcc
	v_fmac_f32_e32 v154, v153, v153
	v_fmac_f32_e32 v114, v127, v127
	v_lshlrev_b32_e32 v149, 2, v143
	v_add_f32_e32 v114, v154, v114
	ds_bpermute_b32 v115, v149, v114
	v_xor_b32_e32 v143, 32, v223
	v_cmp_lt_i32_e32 vcc, v143, v225
	v_lshl_add_u32 v142, s9, 8, v144
	v_lshl_or_b32 v140, s76, 8, v147
	v_cndmask_b32_e32 v143, v223, v143, vcc
	v_lshlrev_b32_e32 v148, 2, v143
	s_waitcnt lgkmcnt(0)
	v_add_f32_e32 v114, v114, v115
	ds_bpermute_b32 v115, v148, v114
	v_ashrrev_i32_e32 v143, 31, v142
	v_lshlrev_b64 v[150:151], 11, v[142:143]
	v_ashrrev_i32_e32 v141, 31, v140
	s_lshl_b32 s28, s76, 2
	v_lshl_add_u64 v[150:151], s[26:27], 0, v[150:151]
	s_ashr_i32 s29, s28, 31
	v_lshl_add_u64 v[150:151], v[140:141], 1, v[150:151]
	v_cvt_pk_bf16_f32 v124, v124, v125
	v_cvt_pk_bf16_f32 v125, v152, v153
	v_cvt_pk_bf16_f32 v116, v118, v119
	v_cvt_pk_bf16_f32 v117, v120, v121
	v_cvt_pk_bf16_f32 v118, v128, v129
	v_cvt_pk_bf16_f32 v119, v126, v127
	global_store_dwordx4 v[150:151], v[122:125], off
	global_store_dwordx4 v[150:151], v[116:119], off offset:256
	s_and_saveexec_b64 s[30:31], s[36:37]
	s_cbranch_execz .LBB0_687
	s_waitcnt lgkmcnt(0)
	v_add_f32_e32 v114, v114, v115
	v_bfe_u32 v115, v114, 16, 1
	v_add3_u32 v116, v114, v115, s63
	v_lshlrev_b64 v[114:115], 5, v[142:143]
	v_lshl_add_u64 v[114:115], s[84:85], 0, v[114:115]
	v_lshl_add_u64 v[114:115], s[28:29], 1, v[114:115]
	s_lshl_b32 s76, s7, 1
	v_lshl_add_u64 v[114:115], v[114:115], 0, s[76:77]
	global_store_short_d16_hi v[114:115], v116, off
